# cache-policy hint: nt on the weight-conversion loads (f32 inputs, read once) and stores (bf16 weights, consumed a layer later) in the FFN-in tails, on v51
# speedup vs baseline: 1.0102x; 1.0056x over previous
.LBB0_263:
	s_or_b64 exec, exec, s[38:39]
	s_mov_b32 s6, 0x2e8ba2e9
	v_mul_hi_i32 v0, v81, s6
	v_lshrrev_b32_e32 v1, 31, v0
	v_ashrrev_i32_e32 v0, 5, v0
	v_add_u32_e32 v1, v0, v1
	s_movk_i32 s6, 0xb0
	v_mul_lo_u32 v0, v1, s6
	v_sub_u32_e32 v0, v81, v0
	v_lshlrev_b32_e32 v0, 5, v0
	v_lshrrev_b32_e32 v83, 3, v75
	v_lshlrev_b32_e32 v2, 2, v75
	v_lshl_or_b32 v34, v1, 6, v83
	v_ashrrev_i32_e32 v1, 31, v0
	s_movk_i32 s6, 0x5800
	v_and_b32_e32 v4, 28, v2
	v_mad_i64_i32 v[2:3], s[20:21], v34, s6, v[24:25]
	v_lshlrev_b64 v[26:27], 2, v[0:1]
	v_lshl_add_u64 v[0:1], v[2:3], 0, v[26:27]
	v_or_b32_e32 v2, 8, v34
	v_or_b32_e32 v8, 16, v34
	v_or_b32_e32 v10, 24, v34
	v_or_b32_e32 v16, 32, v34
	v_or_b32_e32 v18, 40, v34
	s_waitcnt vmcnt(0)
	v_or_b32_e32 v28, 48, v34
	v_or_b32_e32 v30, 56, v34
	v_mad_i64_i32 v[2:3], s[20:21], v2, s6, v[24:25]
	v_mad_i64_i32 v[8:9], s[20:21], v8, s6, v[24:25]
	v_mad_i64_i32 v[10:11], s[20:21], v10, s6, v[24:25]
	v_mad_i64_i32 v[16:17], s[20:21], v16, s6, v[24:25]
	v_mad_i64_i32 v[18:19], s[20:21], v18, s6, v[24:25]
	v_mad_i64_i32 v[28:29], s[20:21], v28, s6, v[24:25]
	v_mad_i64_i32 v[24:25], s[20:21], v30, s6, v[24:25]
	v_lshlrev_b32_e32 v48, 2, v4
	v_lshl_add_u64 v[2:3], v[2:3], 0, v[26:27]
	v_lshl_add_u64 v[8:9], v[8:9], 0, v[26:27]
	v_lshl_add_u64 v[10:11], v[10:11], 0, v[26:27]
	v_lshl_add_u64 v[16:17], v[16:17], 0, v[26:27]
	v_lshl_add_u64 v[18:19], v[18:19], 0, v[26:27]
	v_lshl_add_u64 v[28:29], v[28:29], 0, v[26:27]
	v_lshl_add_u64 v[24:25], v[24:25], 0, v[26:27]
	v_lshl_add_u64 v[0:1], v[0:1], 0, v[48:49]
	v_lshl_add_u64 v[4:5], v[2:3], 0, v[48:49]
	v_lshl_add_u64 v[8:9], v[8:9], 0, v[48:49]
	v_lshl_add_u64 v[12:13], v[10:11], 0, v[48:49]
	v_lshl_add_u64 v[16:17], v[16:17], 0, v[48:49]
	v_lshl_add_u64 v[20:21], v[18:19], 0, v[48:49]
	v_lshl_add_u64 v[28:29], v[28:29], 0, v[48:49]
	v_lshl_add_u64 v[30:31], v[24:25], 0, v[48:49]
	global_load_dwordx4 v[0:3], v[0:1], off nt
	s_nop 0
	global_load_dwordx4 v[4:7], v[4:5], off nt
	s_nop 0
	global_load_dwordx4 v[8:11], v[8:9], off nt
	s_nop 0
	global_load_dwordx4 v[12:15], v[12:13], off nt
	s_nop 0
	global_load_dwordx4 v[16:19], v[16:17], off nt
	s_nop 0
	global_load_dwordx4 v[20:23], v[20:21], off nt
	s_nop 0
	global_load_dwordx4 v[24:27], v[28:29], off nt
	s_nop 0
	global_load_dwordx4 v[28:31], v[30:31], off nt
	v_ashrrev_i32_e32 v35, 31, v34
	v_cmp_ne_u64_e32 vcc, 0, v[32:33]
	v_mov_b32_e32 v70, 1.0
	v_lshl_add_u64 v[32:33], v[34:35], 2, v[32:33]
	v_mov_b32_e32 v72, 1.0
	v_mov_b32_e32 v74, 1.0
	s_and_saveexec_b64 s[38:39], vcc
	s_cbranch_execz .LBB0_265
	global_load_dword v72, v[32:33], off
	global_load_dword v74, v[32:33], off offset:32

.LBB0_273:
	s_or_b64 exec, exec, s[56:57]
	v_pk_mul_f32 v[120:121], v[32:33], v[90:91] op_sel_hi:[1,0]
	ds_write2_b32 v103, v120, v121 offset1:1
	v_pk_mul_f32 v[120:121], v[34:35], v[90:91] op_sel_hi:[1,0]
	ds_write2_b32 v103, v120, v121 offset0:2 offset1:3
	v_pk_mul_f32 v[120:121], v[36:37], v[92:93] op_sel_hi:[1,0]
	ds_write2_b32 v89, v120, v121 offset1:1
	v_pk_mul_f32 v[120:121], v[38:39], v[92:93] op_sel_hi:[1,0]
	ds_write2_b32 v107, v120, v121 offset1:1
	v_pk_mul_f32 v[120:121], v[40:41], v[88:89] op_sel_hi:[1,0]
	ds_write2_b32 v108, v120, v121 offset1:1
	v_pk_mul_f32 v[120:121], v[42:43], v[88:89] op_sel_hi:[1,0]
	ds_write2_b32 v109, v120, v121 offset1:1
	v_pk_mul_f32 v[108:109], v[44:45], v[94:95] op_sel_hi:[1,0]
	ds_write2_b32 v110, v108, v109 offset1:1
	v_pk_mul_f32 v[108:109], v[46:47], v[94:95] op_sel_hi:[1,0]
	ds_write2_b32 v111, v108, v109 offset1:1
	v_pk_mul_f32 v[108:109], v[50:51], v[98:99] op_sel_hi:[1,0]
	ds_write2_b32 v112, v108, v109 offset1:1
	v_pk_mul_f32 v[108:109], v[52:53], v[98:99] op_sel_hi:[1,0]
	ds_write2_b32 v113, v108, v109 offset1:1
	v_pk_mul_f32 v[108:109], v[54:55], v[100:101] op_sel_hi:[1,0]
	ds_write2_b32 v114, v108, v109 offset1:1
	v_pk_mul_f32 v[108:109], v[56:57], v[100:101] op_sel_hi:[1,0]
	ds_write2_b32 v115, v108, v109 offset1:1
	v_pk_mul_f32 v[108:109], v[58:59], v[96:97] op_sel_hi:[1,0]
	s_mov_b32 s6, 0x2e8ba2e9
	ds_write2_b32 v116, v108, v109 offset1:1
	v_pk_mul_f32 v[108:109], v[60:61], v[96:97] op_sel_hi:[1,0]
	v_mul_hi_i32 v69, v106, s6
	ds_write2_b32 v117, v108, v109 offset1:1
	v_pk_mul_f32 v[108:109], v[62:63], v[102:103] op_sel_hi:[1,0]
	v_lshrrev_b32_e32 v104, 31, v69
	v_ashrrev_i32_e32 v69, 5, v69
	ds_write2_b32 v118, v108, v109 offset1:1
	v_pk_mul_f32 v[108:109], v[64:65], v[102:103] op_sel_hi:[1,0]
	v_add_u32_e32 v69, v69, v104
	ds_write2_b32 v119, v108, v109 offset1:1
	s_movk_i32 s6, 0xb0
	v_lshlrev_b32_e32 v104, 6, v69
	v_mul_lo_u32 v69, v69, s6
	s_waitcnt lgkmcnt(0)
	v_sub_u32_e32 v69, v106, v69
	ds_read2_b32 v[108:109], v95 offset1:33
	ds_read2_b32 v[110:111], v95 offset0:66 offset1:99
	ds_read2_b32 v[112:113], v95 offset0:132 offset1:165
	ds_read2_b32 v[114:115], v95 offset0:198 offset1:231
	v_lshlrev_b32_e32 v89, 5, v69
	v_or_b32_e32 v69, v89, v83
	s_movk_i32 s6, 0xaff
	v_cmp_lt_i32_e64 s[38:39], s6, v69
	s_waitcnt lgkmcnt(3)
	v_cvt_pk_bf16_f32 v108, v108, v109
	s_waitcnt lgkmcnt(2)
	v_cvt_pk_bf16_f32 v109, v110, v111
	s_waitcnt lgkmcnt(1)
	v_cvt_pk_bf16_f32 v110, v112, v113
	v_cndmask_b32_e64 v113, 0, v208, s[38:39]
	v_and_b32_e32 v107, 0x60, v89
	v_cndmask_b32_e64 v112, 0, 16, s[38:39]
	v_add_lshl_u32 v69, v113, v69, 1
	v_or_b32_e32 v112, v107, v112
	v_and_b32_e32 v69, 0xffffff00, v69
	v_or3_b32 v112, v112, v69, v93
	v_ashrrev_i32_e32 v113, 31, v112
	v_ashrrev_i32_e32 v105, 31, v104
	v_lshlrev_b64 v[112:113], 11, v[112:113]
	v_lshl_add_u64 v[112:113], v[76:77], 0, v[112:113]
	v_lshlrev_b64 v[104:105], 1, v[104:105]
	v_lshl_add_u64 v[112:113], v[112:113], 0, v[104:105]
	v_mov_b32_e32 v69, v49
	s_waitcnt lgkmcnt(0)
	v_cvt_pk_bf16_f32 v111, v114, v115
	v_lshl_add_u64 v[112:113], v[112:113], 0, v[68:69]
	global_store_dwordx4 v[112:113], v[108:111], off nt
	s_nop 1
	ds_read2_b32 v[108:109], v95 offset0:8 offset1:41
	ds_read2_b32 v[110:111], v95 offset0:74 offset1:107
	ds_read2_b32 v[112:113], v95 offset0:140 offset1:173
	ds_read2_b32 v[114:115], v95 offset0:206 offset1:239
	s_waitcnt lgkmcnt(3)
	v_cvt_pk_bf16_f32 v108, v108, v109
	s_waitcnt lgkmcnt(2)
	v_cvt_pk_bf16_f32 v109, v110, v111
	s_waitcnt lgkmcnt(1)
	v_cvt_pk_bf16_f32 v110, v112, v113
	v_or_b32_e32 v112, v89, v85
	v_cmp_lt_i32_e64 s[38:39], s6, v112
	s_waitcnt lgkmcnt(0)
	v_cvt_pk_bf16_f32 v111, v114, v115
	v_cndmask_b32_e64 v114, 0, v208, s[38:39]
	v_cndmask_b32_e64 v113, 0, 16, s[38:39]
	v_add_lshl_u32 v112, v114, v112, 1
	v_or_b32_e32 v113, v107, v113
	v_and_b32_e32 v112, 0xffffff00, v112
	v_or3_b32 v112, v113, v112, v97
	v_ashrrev_i32_e32 v113, 31, v112
	v_lshlrev_b64 v[112:113], 11, v[112:113]
	v_lshl_add_u64 v[112:113], v[76:77], 0, v[112:113]
	v_lshl_add_u64 v[112:113], v[112:113], 0, v[104:105]
	v_lshl_add_u64 v[112:113], v[112:113], 0, v[68:69]
	global_store_dwordx4 v[112:113], v[108:111], off nt
	s_nop 1
	ds_read2_b32 v[108:109], v95 offset0:16 offset1:49
	ds_read2_b32 v[110:111], v95 offset0:82 offset1:115
	ds_read2_b32 v[112:113], v95 offset0:148 offset1:181
	ds_read2_b32 v[114:115], v95 offset0:214 offset1:247
	s_waitcnt lgkmcnt(3)
	v_cvt_pk_bf16_f32 v108, v108, v109
	s_waitcnt lgkmcnt(2)
	v_cvt_pk_bf16_f32 v109, v110, v111
	s_waitcnt lgkmcnt(1)
	v_cvt_pk_bf16_f32 v110, v112, v113
	v_or_b32_e32 v112, v89, v87
	v_cmp_lt_i32_e64 s[38:39], s6, v112
	s_waitcnt lgkmcnt(0)
	v_cvt_pk_bf16_f32 v111, v114, v115
	v_or_b32_e32 v89, v89, v91
	v_cndmask_b32_e64 v114, 0, v208, s[38:39]
	v_cndmask_b32_e64 v113, 0, 16, s[38:39]
	v_add_lshl_u32 v112, v114, v112, 1
	v_or_b32_e32 v113, v107, v113
	v_and_b32_e32 v112, 0xffffff00, v112
	v_or3_b32 v112, v113, v112, v99
	v_ashrrev_i32_e32 v113, 31, v112
	v_lshlrev_b64 v[112:113], 11, v[112:113]
	v_lshl_add_u64 v[112:113], v[76:77], 0, v[112:113]
	v_cmp_lt_i32_e64 s[38:39], s6, v89
	v_lshl_add_u64 v[112:113], v[112:113], 0, v[104:105]
	v_lshl_add_u64 v[112:113], v[112:113], 0, v[68:69]
	v_cndmask_b32_e64 v116, 0, 16, s[38:39]
	global_store_dwordx4 v[112:113], v[108:111], off nt
	s_nop 1
	v_or_b32_e32 v107, v107, v116
	v_cndmask_b32_e64 v116, 0, v208, s[38:39]
	ds_read2_b32 v[108:109], v95 offset0:24 offset1:57
	ds_read2_b32 v[110:111], v95 offset0:90 offset1:123
	ds_read2_b32 v[112:113], v95 offset0:156 offset1:189
	ds_read2_b32 v[114:115], v95 offset0:222 offset1:255
	v_add_lshl_u32 v89, v116, v89, 1
	v_and_b32_e32 v89, 0xffffff00, v89
	v_or3_b32 v116, v107, v89, v101
	v_ashrrev_i32_e32 v117, 31, v116
	s_waitcnt lgkmcnt(3)
	v_cvt_pk_bf16_f32 v108, v108, v109
	s_waitcnt lgkmcnt(2)
	v_cvt_pk_bf16_f32 v109, v110, v111
	s_waitcnt lgkmcnt(1)
	v_cvt_pk_bf16_f32 v110, v112, v113
	v_lshlrev_b64 v[112:113], 11, v[116:117]
	v_lshl_add_u64 v[112:113], v[76:77], 0, v[112:113]
	v_lshl_add_u64 v[104:105], v[112:113], 0, v[104:105]
	s_waitcnt lgkmcnt(0)
	v_cvt_pk_bf16_f32 v111, v114, v115
	v_lshl_add_u64 v[104:105], v[104:105], 0, v[68:69]
	global_store_dwordx4 v[104:105], v[108:111], off nt
	s_nop 1
	s_waitcnt lgkmcnt(0)
	s_and_b64 s[38:39], vcc, exec

.LBB0_280:
	s_or_b64 exec, exec, s[38:39]
	s_mov_b32 s6, 0x2e8ba2e9
	v_lshl_add_u64 v[58:59], v[32:33], 0, s[48:49]
	v_mul_hi_i32 v32, v106, s6
	v_lshrrev_b32_e32 v33, 31, v32
	v_ashrrev_i32_e32 v32, 5, v32
	v_add_u32_e32 v33, v32, v33
	s_movk_i32 s6, 0xb0
	v_mul_lo_u32 v32, v33, s6
	v_sub_u32_e32 v32, v106, v32
	v_lshlrev_b32_e32 v32, 5, v32
	v_lshl_or_b32 v104, v33, 6, v83
	v_ashrrev_i32_e32 v33, 31, v32
	s_movk_i32 s6, 0x5800
	v_mad_i64_i32 v[34:35], s[20:21], v104, s6, v[58:59]
	v_lshlrev_b64 v[60:61], 2, v[32:33]
	v_lshl_add_u64 v[32:33], v[34:35], 0, v[60:61]
	v_or_b32_e32 v34, 8, v104
	v_or_b32_e32 v40, 16, v104
	v_or_b32_e32 v42, 24, v104
	v_or_b32_e32 v50, 32, v104
	v_or_b32_e32 v52, 40, v104
	v_or_b32_e32 v62, 48, v104
	v_or_b32_e32 v64, 56, v104
	v_mad_i64_i32 v[34:35], s[20:21], v34, s6, v[58:59]
	v_mad_i64_i32 v[40:41], s[20:21], v40, s6, v[58:59]
	v_mad_i64_i32 v[42:43], s[20:21], v42, s6, v[58:59]
	v_mad_i64_i32 v[50:51], s[20:21], v50, s6, v[58:59]
	v_mad_i64_i32 v[52:53], s[20:21], v52, s6, v[58:59]
	v_mad_i64_i32 v[62:63], s[20:21], v62, s6, v[58:59]
	v_mad_i64_i32 v[58:59], s[20:21], v64, s6, v[58:59]
	v_lshl_add_u64 v[34:35], v[34:35], 0, v[60:61]
	v_lshl_add_u64 v[40:41], v[40:41], 0, v[60:61]
	v_lshl_add_u64 v[42:43], v[42:43], 0, v[60:61]
	v_lshl_add_u64 v[50:51], v[50:51], 0, v[60:61]
	v_lshl_add_u64 v[52:53], v[52:53], 0, v[60:61]
	v_lshl_add_u64 v[62:63], v[62:63], 0, v[60:61]
	v_lshl_add_u64 v[58:59], v[58:59], 0, v[60:61]
	v_lshl_add_u64 v[32:33], v[32:33], 0, v[48:49]
	v_lshl_add_u64 v[36:37], v[34:35], 0, v[48:49]
	v_lshl_add_u64 v[40:41], v[40:41], 0, v[48:49]
	v_lshl_add_u64 v[44:45], v[42:43], 0, v[48:49]
	v_lshl_add_u64 v[50:51], v[50:51], 0, v[48:49]
	v_lshl_add_u64 v[54:55], v[52:53], 0, v[48:49]
	v_lshl_add_u64 v[62:63], v[62:63], 0, v[48:49]
	v_lshl_add_u64 v[64:65], v[58:59], 0, v[48:49]
	global_load_dwordx4 v[32:35], v[32:33], off nt
	s_nop 0
	global_load_dwordx4 v[36:39], v[36:37], off nt
	s_nop 0
	global_load_dwordx4 v[40:43], v[40:41], off nt
	s_nop 0
	global_load_dwordx4 v[44:47], v[44:45], off nt
	s_nop 0
	global_load_dwordx4 v[50:53], v[50:51], off nt
	s_nop 0
	global_load_dwordx4 v[54:57], v[54:55], off nt
	s_nop 0
	global_load_dwordx4 v[58:61], v[62:63], off nt
	s_nop 0
	global_load_dwordx4 v[62:65], v[64:65], off nt
	v_lshl_add_u64 v[108:109], s[24:25], 2, v[88:89]
	v_ashrrev_i32_e32 v105, 31, v104
	v_cmp_ne_u64_e64 s[38:39], 0, v[88:89]
	v_mov_b32_e32 v88, 1.0
	v_lshl_add_u64 v[104:105], v[104:105], 2, v[108:109]
	v_mov_b32_e32 v90, 1.0
	v_mov_b32_e32 v92, 1.0
	s_and_saveexec_b64 s[56:57], s[38:39]
	s_cbranch_execz .LBB0_282
	global_load_dword v90, v[104:105], off
	global_load_dword v92, v[104:105], off offset:32

.LBB0_289:
	s_or_b64 exec, exec, s[54:55]
	s_mov_b32 s6, 0x2e8ba2e9
	v_mul_hi_i32 v69, v81, s6
	s_waitcnt vmcnt(1)
	v_pk_mul_f32 v[108:109], v[72:73], v[0:1] op_sel_hi:[0,1]
	v_lshrrev_b32_e32 v89, 31, v69
	v_ashrrev_i32_e32 v69, 5, v69
	ds_write2_b32 v103, v108, v109 offset1:1
	v_pk_mul_f32 v[108:109], v[72:73], v[2:3] op_sel_hi:[0,1]
	v_add_u32_e32 v69, v69, v89
	ds_write2_b32 v103, v108, v109 offset0:2 offset1:3
	s_waitcnt vmcnt(0)
	v_pk_mul_f32 v[108:109], v[74:75], v[4:5] op_sel_hi:[0,1]
	v_add_u32_e32 v89, 0x420, v103
	ds_write2_b32 v89, v108, v109 offset1:1
	v_pk_mul_f32 v[108:109], v[74:75], v[6:7] op_sel_hi:[0,1]
	v_add_u32_e32 v107, 0x428, v103
	ds_write2_b32 v107, v108, v109 offset1:1
	v_pk_mul_f32 v[110:111], v[70:71], v[8:9] op_sel_hi:[0,1]
	v_add_u32_e32 v108, 0x840, v103
	ds_write2_b32 v108, v110, v111 offset1:1
	v_pk_mul_f32 v[110:111], v[70:71], v[10:11] op_sel_hi:[0,1]
	v_add_u32_e32 v109, 0x848, v103
	ds_write2_b32 v109, v110, v111 offset1:1
	v_pk_mul_f32 v[112:113], v[78:79], v[12:13] op_sel_hi:[0,1]
	v_add_u32_e32 v110, 0xc60, v103
	ds_write2_b32 v110, v112, v113 offset1:1
	v_pk_mul_f32 v[112:113], v[78:79], v[14:15] op_sel_hi:[0,1]
	v_add_u32_e32 v111, 0xc68, v103
	ds_write2_b32 v111, v112, v113 offset1:1
	v_pk_mul_f32 v[114:115], v[82:83], v[16:17] op_sel_hi:[0,1]
	v_add_u32_e32 v112, 0x1080, v103
	ds_write2_b32 v112, v114, v115 offset1:1
	v_pk_mul_f32 v[114:115], v[82:83], v[18:19] op_sel_hi:[0,1]
	v_add_u32_e32 v113, 0x1088, v103
	ds_write2_b32 v113, v114, v115 offset1:1
	v_pk_mul_f32 v[116:117], v[84:85], v[20:21] op_sel_hi:[0,1]
	v_add_u32_e32 v114, 0x14a0, v103
	ds_write2_b32 v114, v116, v117 offset1:1
	v_pk_mul_f32 v[116:117], v[84:85], v[22:23] op_sel_hi:[0,1]
	v_add_u32_e32 v115, 0x14a8, v103
	ds_write2_b32 v115, v116, v117 offset1:1
	v_pk_mul_f32 v[118:119], v[80:81], v[24:25] op_sel_hi:[0,1]
	v_add_u32_e32 v116, 0x18c0, v103
	ds_write2_b32 v116, v118, v119 offset1:1
	v_pk_mul_f32 v[118:119], v[80:81], v[26:27] op_sel_hi:[0,1]
	v_add_u32_e32 v117, 0x18c8, v103
	ds_write2_b32 v117, v118, v119 offset1:1
	v_pk_mul_f32 v[122:123], v[86:87], v[28:29] op_sel_hi:[0,1]
	v_add_u32_e32 v118, 0x1ce0, v103
	ds_write2_b32 v118, v122, v123 offset1:1
	v_pk_mul_f32 v[122:123], v[86:87], v[30:31] op_sel_hi:[0,1]
	v_add_u32_e32 v119, 0x1ce8, v103
	ds_write2_b32 v119, v122, v123 offset1:1
	s_movk_i32 s6, 0xb0
	v_lshlrev_b32_e32 v104, 6, v69
	v_mul_lo_u32 v69, v69, s6
	s_waitcnt lgkmcnt(0)
	v_sub_u32_e32 v69, v81, v69
	ds_read2_b32 v[122:123], v95 offset1:33
	ds_read2_b32 v[124:125], v95 offset0:66 offset1:99
	ds_read2_b32 v[126:127], v95 offset0:132 offset1:165
	ds_read2_b32 v[128:129], v95 offset0:198 offset1:231
	v_lshlrev_b32_e32 v121, 5, v69
	v_or_b32_e32 v69, v121, v83
	s_movk_i32 s6, 0xaff
	v_cmp_lt_i32_e64 s[38:39], s6, v69
	s_waitcnt lgkmcnt(3)
	v_cvt_pk_bf16_f32 v122, v122, v123
	s_waitcnt lgkmcnt(2)
	v_cvt_pk_bf16_f32 v123, v124, v125
	s_waitcnt lgkmcnt(1)
	v_cvt_pk_bf16_f32 v124, v126, v127
	v_cndmask_b32_e64 v127, 0, v208, s[38:39]
	v_and_b32_e32 v130, 0x60, v121
	v_cndmask_b32_e64 v126, 0, 16, s[38:39]
	v_add_lshl_u32 v69, v127, v69, 1
	v_or_b32_e32 v126, v130, v126
	v_and_b32_e32 v69, 0xffffff00, v69
	v_or3_b32 v126, v126, v69, v93
	v_ashrrev_i32_e32 v127, 31, v126
	v_ashrrev_i32_e32 v105, 31, v104
	v_lshlrev_b64 v[126:127], 11, v[126:127]
	v_lshl_add_u64 v[126:127], v[66:67], 0, v[126:127]
	v_lshlrev_b64 v[104:105], 1, v[104:105]
	v_lshl_add_u64 v[126:127], v[126:127], 0, v[104:105]
	v_mov_b32_e32 v69, v49
	s_waitcnt lgkmcnt(0)
	v_cvt_pk_bf16_f32 v125, v128, v129
	v_lshl_add_u64 v[126:127], v[126:127], 0, v[68:69]
	global_store_dwordx4 v[126:127], v[122:125], off nt
	s_nop 1
	ds_read2_b32 v[122:123], v95 offset0:8 offset1:41
	ds_read2_b32 v[124:125], v95 offset0:74 offset1:107
	ds_read2_b32 v[126:127], v95 offset0:140 offset1:173
	ds_read2_b32 v[128:129], v95 offset0:206 offset1:239
	s_waitcnt lgkmcnt(3)
	v_cvt_pk_bf16_f32 v122, v122, v123
	s_waitcnt lgkmcnt(2)
	v_cvt_pk_bf16_f32 v123, v124, v125
	s_waitcnt lgkmcnt(1)
	v_cvt_pk_bf16_f32 v124, v126, v127
	v_or_b32_e32 v126, v121, v85
	v_cmp_lt_i32_e64 s[38:39], s6, v126
	s_waitcnt lgkmcnt(0)
	v_cvt_pk_bf16_f32 v125, v128, v129
	v_cndmask_b32_e64 v128, 0, v208, s[38:39]
	v_cndmask_b32_e64 v127, 0, 16, s[38:39]
	v_add_lshl_u32 v126, v128, v126, 1
	v_or_b32_e32 v127, v130, v127
	v_and_b32_e32 v126, 0xffffff00, v126
	v_or3_b32 v126, v127, v126, v97
	v_ashrrev_i32_e32 v127, 31, v126
	v_lshlrev_b64 v[126:127], 11, v[126:127]
	v_lshl_add_u64 v[126:127], v[66:67], 0, v[126:127]
	v_lshl_add_u64 v[126:127], v[126:127], 0, v[104:105]
	v_lshl_add_u64 v[126:127], v[126:127], 0, v[68:69]
	global_store_dwordx4 v[126:127], v[122:125], off nt
	s_nop 1
	ds_read2_b32 v[122:123], v95 offset0:16 offset1:49
	ds_read2_b32 v[124:125], v95 offset0:82 offset1:115
	ds_read2_b32 v[126:127], v95 offset0:148 offset1:181
	ds_read2_b32 v[128:129], v95 offset0:214 offset1:247
	s_waitcnt lgkmcnt(3)
	v_cvt_pk_bf16_f32 v122, v122, v123
	s_waitcnt lgkmcnt(2)
	v_cvt_pk_bf16_f32 v123, v124, v125
	s_waitcnt lgkmcnt(1)
	v_cvt_pk_bf16_f32 v124, v126, v127
	v_or_b32_e32 v126, v121, v87
	v_cmp_lt_i32_e64 s[38:39], s6, v126
	s_waitcnt lgkmcnt(0)
	v_cvt_pk_bf16_f32 v125, v128, v129
	v_or_b32_e32 v121, v121, v91
	v_cndmask_b32_e64 v128, 0, v208, s[38:39]
	v_cndmask_b32_e64 v127, 0, 16, s[38:39]
	v_add_lshl_u32 v126, v128, v126, 1
	v_or_b32_e32 v127, v130, v127
	v_and_b32_e32 v126, 0xffffff00, v126
	v_or3_b32 v126, v127, v126, v99
	v_ashrrev_i32_e32 v127, 31, v126
	v_lshlrev_b64 v[126:127], 11, v[126:127]
	v_lshl_add_u64 v[126:127], v[66:67], 0, v[126:127]
	v_cmp_lt_i32_e64 s[38:39], s6, v121
	v_lshl_add_u64 v[126:127], v[126:127], 0, v[104:105]
	v_lshl_add_u64 v[126:127], v[126:127], 0, v[68:69]
	v_cndmask_b32_e64 v131, 0, 16, s[38:39]
	global_store_dwordx4 v[126:127], v[122:125], off nt
	s_nop 1
	v_or_b32_e32 v130, v130, v131
	v_cndmask_b32_e64 v131, 0, v208, s[38:39]
	ds_read2_b32 v[122:123], v95 offset0:24 offset1:57
	ds_read2_b32 v[124:125], v95 offset0:90 offset1:123
	ds_read2_b32 v[126:127], v95 offset0:156 offset1:189
	ds_read2_b32 v[128:129], v95 offset0:222 offset1:255
	v_add_lshl_u32 v121, v131, v121, 1
	v_and_b32_e32 v121, 0xffffff00, v121
	v_or3_b32 v130, v130, v121, v101
	v_ashrrev_i32_e32 v131, 31, v130
	s_waitcnt lgkmcnt(3)
	v_cvt_pk_bf16_f32 v122, v122, v123
	s_waitcnt lgkmcnt(2)
	v_cvt_pk_bf16_f32 v123, v124, v125
	s_waitcnt lgkmcnt(1)
	v_cvt_pk_bf16_f32 v124, v126, v127
	v_lshlrev_b64 v[126:127], 11, v[130:131]
	v_lshl_add_u64 v[126:127], v[66:67], 0, v[126:127]
	v_lshl_add_u64 v[104:105], v[126:127], 0, v[104:105]
	s_waitcnt lgkmcnt(0)
	v_cvt_pk_bf16_f32 v125, v128, v129
	v_lshl_add_u64 v[104:105], v[104:105], 0, v[68:69]
	global_store_dwordx4 v[104:105], v[122:125], off nt
	s_nop 1
	s_waitcnt lgkmcnt(0)
	s_mov_b64 s[38:39], 0
	s_and_saveexec_b64 s[54:55], vcc
	s_cbranch_execz .LBB0_274
	v_readlane_b32 s6, v255, 4
	s_nop 1
	v_add_u32_e32 v69, s6, v120
	v_cmp_gt_i32_e32 vcc, s33, v69
	s_and_saveexec_b64 s[56:57], vcc
	s_cbranch_execz .LBB0_273
	s_movk_i32 s6, 0xaff
	v_cmp_lt_i32_e64 s[38:39], s6, v69
	s_and_saveexec_b64 s[20:21], s[38:39]
	s_xor_b64 s[38:39], exec, s[20:21]
	s_cbranch_execz .LBB0_293
	s_load_dwordx2 s[58:59], s[0:1], 48
	s_waitcnt lgkmcnt(0)
	s_load_dwordx2 s[60:61], s[0:1], 40
	s_waitcnt lgkmcnt(0)
	v_add_u32_e32 v81, 0xfffff500, v69

.LBB0_295:
	s_or_b64 exec, exec, s[38:39]
	s_mov_b32 s6, 0x2e8ba2e9
	v_lshl_add_u64 v[24:25], v[0:1], 0, s[48:49]
	v_mul_hi_i32 v0, v81, s6
	v_lshrrev_b32_e32 v1, 31, v0
	v_ashrrev_i32_e32 v0, 5, v0
	v_add_u32_e32 v1, v0, v1
	s_movk_i32 s6, 0xb0
	v_mul_lo_u32 v0, v1, s6
	v_sub_u32_e32 v0, v81, v0
	v_lshlrev_b32_e32 v0, 5, v0
	v_lshl_or_b32 v104, v1, 6, v83
	v_ashrrev_i32_e32 v1, 31, v0
	s_movk_i32 s6, 0x5800
	v_mad_i64_i32 v[2:3], s[20:21], v104, s6, v[24:25]
	v_lshlrev_b64 v[26:27], 2, v[0:1]
	v_lshl_add_u64 v[0:1], v[2:3], 0, v[26:27]
	v_or_b32_e32 v2, 8, v104
	v_or_b32_e32 v8, 16, v104
	v_or_b32_e32 v10, 24, v104
	v_or_b32_e32 v16, 32, v104
	v_or_b32_e32 v18, 40, v104
	v_or_b32_e32 v28, 48, v104
	v_or_b32_e32 v30, 56, v104
	v_mad_i64_i32 v[2:3], s[20:21], v2, s6, v[24:25]
	v_mad_i64_i32 v[8:9], s[20:21], v8, s6, v[24:25]
	v_mad_i64_i32 v[10:11], s[20:21], v10, s6, v[24:25]
	v_mad_i64_i32 v[16:17], s[20:21], v16, s6, v[24:25]
	v_mad_i64_i32 v[18:19], s[20:21], v18, s6, v[24:25]
	v_mad_i64_i32 v[28:29], s[20:21], v28, s6, v[24:25]
	v_mad_i64_i32 v[24:25], s[20:21], v30, s6, v[24:25]
	v_lshl_add_u64 v[2:3], v[2:3], 0, v[26:27]
	v_lshl_add_u64 v[8:9], v[8:9], 0, v[26:27]
	v_lshl_add_u64 v[10:11], v[10:11], 0, v[26:27]
	v_lshl_add_u64 v[16:17], v[16:17], 0, v[26:27]
	v_lshl_add_u64 v[18:19], v[18:19], 0, v[26:27]
	v_lshl_add_u64 v[28:29], v[28:29], 0, v[26:27]
	v_lshl_add_u64 v[24:25], v[24:25], 0, v[26:27]
	v_lshl_add_u64 v[0:1], v[0:1], 0, v[48:49]
	v_lshl_add_u64 v[4:5], v[2:3], 0, v[48:49]
	v_lshl_add_u64 v[8:9], v[8:9], 0, v[48:49]
	v_lshl_add_u64 v[12:13], v[10:11], 0, v[48:49]
	v_lshl_add_u64 v[16:17], v[16:17], 0, v[48:49]
	v_lshl_add_u64 v[20:21], v[18:19], 0, v[48:49]
	v_lshl_add_u64 v[28:29], v[28:29], 0, v[48:49]
	v_lshl_add_u64 v[30:31], v[24:25], 0, v[48:49]
	global_load_dwordx4 v[0:3], v[0:1], off nt
	s_nop 0
	global_load_dwordx4 v[4:7], v[4:5], off nt
	s_nop 0
	global_load_dwordx4 v[8:11], v[8:9], off nt
	s_nop 0
	global_load_dwordx4 v[12:15], v[12:13], off nt
	s_nop 0
	global_load_dwordx4 v[16:19], v[16:17], off nt
	s_nop 0
	global_load_dwordx4 v[20:23], v[20:21], off nt
	s_nop 0
	global_load_dwordx4 v[24:27], v[28:29], off nt
	s_nop 0
	global_load_dwordx4 v[28:31], v[30:31], off nt
	v_lshl_add_u64 v[120:121], s[24:25], 2, v[70:71]
	v_ashrrev_i32_e32 v105, 31, v104
	v_cmp_ne_u64_e64 s[38:39], 0, v[70:71]
	v_mov_b32_e32 v70, 1.0
	v_lshl_add_u64 v[104:105], v[104:105], 2, v[120:121]
	v_mov_b32_e32 v72, 1.0
	v_mov_b32_e32 v74, 1.0
	s_and_saveexec_b64 s[58:59], s[38:39]
	s_cbranch_execz .LBB0_297
	global_load_dword v72, v[104:105], off
	global_load_dword v74, v[104:105], off offset:32

.LBB0_307:
	s_waitcnt vmcnt(5)
	v_ashrrev_i32_e32 v8, 31, v7
	v_lshrrev_b32_e32 v8, 25, v8
	v_add_u32_e32 v8, v7, v8
	v_ashrrev_i32_e32 v8, 7, v8
	v_ashrrev_i32_e32 v9, 31, v8
	v_lshlrev_b32_e32 v10, 11, v8
	v_lshlrev_b64 v[8:9], 11, v[8:9]
	v_sub_u32_e32 v10, v6, v10
	v_lshl_add_u64 v[8:9], s[46:47], 0, v[8:9]
	v_ashrrev_i32_e32 v11, 31, v10
	v_add_u32_e32 v7, s80, v7
	v_lshl_add_u64 v[8:9], v[8:9], 0, v[10:11]
	global_store_dwordx4 v[8:9], v[0:3], off nt
	s_nop 1
	v_cmp_lt_i32_e64 s[38:39], s81, v7
	s_or_b64 s[48:49], s[38:39], s[48:49]
	v_add_u32_e32 v6, s6, v6
	s_andn2_b64 exec, exec, s[48:49]
	s_cbranch_execnz .LBB0_307

.LBB0_310:
	s_waitcnt vmcnt(5)
	v_ashrrev_i32_e32 v10, 31, v7
	v_lshrrev_b32_e32 v10, 28, v10
	v_add_u32_e32 v10, v7, v10
	v_mov_b64_e32 v[8:9], s[44:45]
	v_ashrrev_i32_e32 v10, 4, v10
	v_mad_i64_i32 v[8:9], s[20:21], v10, s95, v[8:9]
	v_lshlrev_b32_e32 v10, 8, v10
	v_sub_u32_e32 v10, v6, v10
	v_ashrrev_i32_e32 v11, 31, v10
	v_add_u32_e32 v7, s80, v7
	v_lshl_add_u64 v[8:9], v[8:9], 0, v[10:11]
	global_store_dwordx4 v[8:9], v[0:3], off nt
	s_nop 1
	v_cmp_lt_i32_e32 vcc, s81, v7
	s_or_b64 s[46:47], vcc, s[46:47]
	v_add_u32_e32 v6, s6, v6
	s_andn2_b64 exec, exec, s[46:47]
	s_cbranch_execnz .LBB0_310

.LBB0_313:
	s_waitcnt vmcnt(5)
	v_ashrrev_i32_e32 v8, 31, v4
	v_lshrrev_b32_e32 v8, 27, v8
	v_add_u32_e32 v8, v4, v8
	v_mov_b64_e32 v[6:7], s[38:39]
	v_ashrrev_i32_e32 v8, 5, v8
	v_mad_i64_i32 v[6:7], s[20:21], v8, s95, v[6:7]
	v_lshlrev_b32_e32 v8, 9, v8
	v_sub_u32_e32 v8, v5, v8
	v_ashrrev_i32_e32 v9, 31, v8
	v_add_u32_e32 v4, s80, v4
	v_lshl_add_u64 v[6:7], v[6:7], 0, v[8:9]
	global_store_dwordx4 v[6:7], v[0:3], off nt
	s_nop 1
	v_cmp_lt_i32_e32 vcc, s84, v4
	s_or_b64 s[42:43], vcc, s[42:43]
	v_add_u32_e32 v5, s6, v5
	s_andn2_b64 exec, exec, s[42:43]
	s_cbranch_execnz .LBB0_313

.LBB0_320:
	s_or_b64 exec, exec, s[38:39]
	s_mov_b32 s6, 0x2e8ba2e9
	v_mul_hi_i32 v0, v79, s6
	v_lshrrev_b32_e32 v1, 31, v0
	v_ashrrev_i32_e32 v0, 5, v0
	v_add_u32_e32 v1, v0, v1
	s_movk_i32 s6, 0xb0
	v_mul_lo_u32 v0, v1, s6
	v_sub_u32_e32 v0, v79, v0
	v_lshlrev_b32_e32 v0, 5, v0
	v_lshrrev_b32_e32 v81, 3, v75
	v_lshlrev_b32_e32 v2, 2, v75
	v_lshl_or_b32 v34, v1, 6, v81
	v_ashrrev_i32_e32 v1, 31, v0
	s_movk_i32 s6, 0x5800
	v_and_b32_e32 v4, 28, v2
	v_mad_i64_i32 v[2:3], s[20:21], v34, s6, v[24:25]
	v_lshlrev_b64 v[26:27], 2, v[0:1]
	v_lshl_add_u64 v[0:1], v[2:3], 0, v[26:27]
	v_or_b32_e32 v2, 8, v34
	v_or_b32_e32 v8, 16, v34
	v_or_b32_e32 v10, 24, v34
	v_or_b32_e32 v16, 32, v34
	v_or_b32_e32 v18, 40, v34
	s_waitcnt vmcnt(0)
	v_or_b32_e32 v28, 48, v34
	v_or_b32_e32 v30, 56, v34
	v_mad_i64_i32 v[2:3], s[20:21], v2, s6, v[24:25]
	v_mad_i64_i32 v[8:9], s[20:21], v8, s6, v[24:25]
	v_mad_i64_i32 v[10:11], s[20:21], v10, s6, v[24:25]
	v_mad_i64_i32 v[16:17], s[20:21], v16, s6, v[24:25]
	v_mad_i64_i32 v[18:19], s[20:21], v18, s6, v[24:25]
	v_mad_i64_i32 v[28:29], s[20:21], v28, s6, v[24:25]
	v_mad_i64_i32 v[24:25], s[20:21], v30, s6, v[24:25]
	v_lshlrev_b32_e32 v48, 2, v4
	v_lshl_add_u64 v[2:3], v[2:3], 0, v[26:27]
	v_lshl_add_u64 v[8:9], v[8:9], 0, v[26:27]
	v_lshl_add_u64 v[10:11], v[10:11], 0, v[26:27]
	v_lshl_add_u64 v[16:17], v[16:17], 0, v[26:27]
	v_lshl_add_u64 v[18:19], v[18:19], 0, v[26:27]
	v_lshl_add_u64 v[28:29], v[28:29], 0, v[26:27]
	v_lshl_add_u64 v[24:25], v[24:25], 0, v[26:27]
	v_lshl_add_u64 v[0:1], v[0:1], 0, v[48:49]
	v_lshl_add_u64 v[4:5], v[2:3], 0, v[48:49]
	v_lshl_add_u64 v[8:9], v[8:9], 0, v[48:49]
	v_lshl_add_u64 v[12:13], v[10:11], 0, v[48:49]
	v_lshl_add_u64 v[16:17], v[16:17], 0, v[48:49]
	v_lshl_add_u64 v[20:21], v[18:19], 0, v[48:49]
	v_lshl_add_u64 v[28:29], v[28:29], 0, v[48:49]
	v_lshl_add_u64 v[30:31], v[24:25], 0, v[48:49]
	global_load_dwordx4 v[0:3], v[0:1], off nt
	s_nop 0
	global_load_dwordx4 v[4:7], v[4:5], off nt
	s_nop 0
	global_load_dwordx4 v[8:11], v[8:9], off nt
	s_nop 0
	global_load_dwordx4 v[12:15], v[12:13], off nt
	s_nop 0
	global_load_dwordx4 v[16:19], v[16:17], off nt
	s_nop 0
	global_load_dwordx4 v[20:23], v[20:21], off nt
	s_nop 0
	global_load_dwordx4 v[24:27], v[28:29], off nt
	s_nop 0
	global_load_dwordx4 v[28:31], v[30:31], off nt
	v_ashrrev_i32_e32 v35, 31, v34
	v_cmp_ne_u64_e32 vcc, 0, v[32:33]
	v_mov_b32_e32 v70, 1.0
	v_lshl_add_u64 v[32:33], v[34:35], 2, v[32:33]
	v_mov_b32_e32 v72, 1.0
	v_mov_b32_e32 v74, 1.0
	s_and_saveexec_b64 s[38:39], vcc
	s_cbranch_execz .LBB0_322
	global_load_dword v72, v[32:33], off
	global_load_dword v74, v[32:33], off offset:32

.LBB0_330:
	s_or_b64 exec, exec, s[54:55]
	s_mov_b32 s6, 0x2e8ba2e9
	v_mul_hi_i32 v69, v101, s6
	v_lshrrev_b32_e32 v104, 31, v69
	v_ashrrev_i32_e32 v69, 5, v69
	v_add_u32_e32 v69, v69, v104
	v_pk_mul_f32 v[104:105], v[32:33], v[90:91] op_sel_hi:[1,0]
	ds_write2_b32 v99, v104, v105 offset1:1
	v_pk_mul_f32 v[104:105], v[34:35], v[90:91] op_sel_hi:[1,0]
	ds_write2_b32 v99, v104, v105 offset0:2 offset1:3
	v_pk_mul_f32 v[104:105], v[36:37], v[92:93] op_sel_hi:[1,0]
	ds_write2_b32 v89, v104, v105 offset1:1
	v_pk_mul_f32 v[104:105], v[38:39], v[92:93] op_sel_hi:[1,0]
	ds_write2_b32 v103, v104, v105 offset1:1
	v_pk_mul_f32 v[104:105], v[40:41], v[88:89] op_sel_hi:[1,0]
	ds_write2_b32 v106, v104, v105 offset1:1
	v_pk_mul_f32 v[104:105], v[42:43], v[88:89] op_sel_hi:[1,0]
	ds_write2_b32 v107, v104, v105 offset1:1
	v_pk_mul_f32 v[104:105], v[44:45], v[94:95] op_sel_hi:[1,0]
	ds_write2_b32 v108, v104, v105 offset1:1
	v_pk_mul_f32 v[104:105], v[46:47], v[94:95] op_sel_hi:[1,0]
	ds_write2_b32 v109, v104, v105 offset1:1
	v_pk_mul_f32 v[104:105], v[50:51], v[98:99] op_sel_hi:[1,0]
	ds_write2_b32 v110, v104, v105 offset1:1
	v_pk_mul_f32 v[104:105], v[52:53], v[98:99] op_sel_hi:[1,0]
	ds_write2_b32 v111, v104, v105 offset1:1
	v_pk_mul_f32 v[104:105], v[54:55], v[100:101] op_sel_hi:[1,0]
	ds_write2_b32 v112, v104, v105 offset1:1
	v_pk_mul_f32 v[104:105], v[56:57], v[100:101] op_sel_hi:[1,0]
	ds_write2_b32 v113, v104, v105 offset1:1
	v_pk_mul_f32 v[104:105], v[58:59], v[96:97] op_sel_hi:[1,0]
	ds_write2_b32 v114, v104, v105 offset1:1
	v_pk_mul_f32 v[104:105], v[60:61], v[96:97] op_sel_hi:[1,0]
	ds_write2_b32 v115, v104, v105 offset1:1
	v_pk_mul_f32 v[104:105], v[62:63], v[102:103] op_sel_hi:[1,0]
	ds_write2_b32 v116, v104, v105 offset1:1
	v_pk_mul_f32 v[104:105], v[64:65], v[102:103] op_sel_hi:[1,0]
	ds_write2_b32 v117, v104, v105 offset1:1
	s_movk_i32 s6, 0xb0
	v_lshlrev_b32_e32 v118, 6, v69
	v_mul_lo_u32 v69, v69, s6
	s_waitcnt lgkmcnt(0)
	v_sub_u32_e32 v69, v101, v69
	ds_read2_b32 v[104:105], v91 offset1:33
	ds_read2_b32 v[106:107], v91 offset0:66 offset1:99
	ds_read2_b32 v[108:109], v91 offset0:132 offset1:165
	ds_read2_b32 v[110:111], v91 offset0:198 offset1:231
	v_lshlrev_b32_e32 v89, 5, v69
	v_or_b32_e32 v69, v89, v81
	s_movk_i32 s6, 0xaff
	v_cmp_lt_i32_e64 s[38:39], s6, v69
	s_waitcnt lgkmcnt(3)
	v_cvt_pk_bf16_f32 v104, v104, v105
	s_waitcnt lgkmcnt(2)
	v_cvt_pk_bf16_f32 v105, v106, v107
	s_waitcnt lgkmcnt(1)
	v_cvt_pk_bf16_f32 v106, v108, v109
	v_cndmask_b32_e64 v109, 0, v208, s[38:39]
	v_and_b32_e32 v103, 0x60, v89
	v_cndmask_b32_e64 v108, 0, 16, s[38:39]
	v_add_lshl_u32 v69, v109, v69, 1
	v_or_b32_e32 v108, v103, v108
	v_and_b32_e32 v69, 0xffffff00, v69
	v_or3_b32 v108, v108, v69, v87
	v_ashrrev_i32_e32 v109, 31, v108
	v_ashrrev_i32_e32 v119, 31, v118
	v_lshlrev_b64 v[108:109], 11, v[108:109]
	s_waitcnt lgkmcnt(0)
	v_cvt_pk_bf16_f32 v107, v110, v111
	v_lshl_add_u64 v[108:109], v[76:77], 0, v[108:109]
	v_lshlrev_b64 v[110:111], 1, v[118:119]
	v_lshl_add_u64 v[108:109], v[108:109], 0, v[110:111]
	v_mov_b32_e32 v69, v49
	v_lshl_add_u64 v[108:109], v[108:109], 0, v[68:69]
	global_store_dwordx4 v[108:109], v[104:107], off nt
	s_nop 1
	ds_read2_b32 v[104:105], v91 offset0:8 offset1:41
	ds_read2_b32 v[106:107], v91 offset0:74 offset1:107
	ds_read2_b32 v[108:109], v91 offset0:140 offset1:173
	ds_read2_b32 v[112:113], v91 offset0:206 offset1:239
	s_waitcnt lgkmcnt(3)
	v_cvt_pk_bf16_f32 v104, v104, v105
	s_waitcnt lgkmcnt(2)
	v_cvt_pk_bf16_f32 v105, v106, v107
	s_waitcnt lgkmcnt(1)
	v_cvt_pk_bf16_f32 v106, v108, v109
	v_or_b32_e32 v108, v89, v75
	v_cmp_lt_i32_e64 s[38:39], s6, v108
	s_waitcnt lgkmcnt(0)
	v_cvt_pk_bf16_f32 v107, v112, v113
	v_cndmask_b32_e64 v112, 0, v208, s[38:39]
	v_cndmask_b32_e64 v109, 0, 16, s[38:39]
	v_add_lshl_u32 v108, v112, v108, 1
	v_or_b32_e32 v109, v103, v109
	v_and_b32_e32 v108, 0xffffff00, v108
	v_or3_b32 v108, v109, v108, v93
	v_ashrrev_i32_e32 v109, 31, v108
	v_lshlrev_b64 v[108:109], 11, v[108:109]
	v_lshl_add_u64 v[108:109], v[76:77], 0, v[108:109]
	v_lshl_add_u64 v[108:109], v[108:109], 0, v[110:111]
	v_lshl_add_u64 v[108:109], v[108:109], 0, v[68:69]
	global_store_dwordx4 v[108:109], v[104:107], off nt
	s_nop 1
	ds_read2_b32 v[104:105], v91 offset0:16 offset1:49
	ds_read2_b32 v[106:107], v91 offset0:82 offset1:115
	ds_read2_b32 v[108:109], v91 offset0:148 offset1:181
	ds_read2_b32 v[112:113], v91 offset0:214 offset1:247
	s_waitcnt lgkmcnt(3)
	v_cvt_pk_bf16_f32 v104, v104, v105
	s_waitcnt lgkmcnt(2)
	v_cvt_pk_bf16_f32 v105, v106, v107
	s_waitcnt lgkmcnt(1)
	v_cvt_pk_bf16_f32 v106, v108, v109
	v_or_b32_e32 v108, v89, v83
	v_cmp_lt_i32_e64 s[38:39], s6, v108
	s_waitcnt lgkmcnt(0)
	v_cvt_pk_bf16_f32 v107, v112, v113
	v_or_b32_e32 v89, v89, v85
	v_cndmask_b32_e64 v112, 0, v208, s[38:39]
	v_cndmask_b32_e64 v109, 0, 16, s[38:39]
	v_add_lshl_u32 v108, v112, v108, 1
	v_or_b32_e32 v109, v103, v109
	v_and_b32_e32 v108, 0xffffff00, v108
	v_or3_b32 v108, v109, v108, v95
	v_ashrrev_i32_e32 v109, 31, v108
	v_lshlrev_b64 v[108:109], 11, v[108:109]
	v_lshl_add_u64 v[108:109], v[76:77], 0, v[108:109]
	v_cmp_lt_i32_e64 s[38:39], s6, v89
	v_lshl_add_u64 v[108:109], v[108:109], 0, v[110:111]
	v_lshl_add_u64 v[108:109], v[108:109], 0, v[68:69]
	v_cndmask_b32_e64 v114, 0, 16, s[38:39]
	global_store_dwordx4 v[108:109], v[104:107], off nt
	s_nop 1
	v_or_b32_e32 v103, v103, v114
	v_cndmask_b32_e64 v114, 0, v208, s[38:39]
	ds_read2_b32 v[104:105], v91 offset0:24 offset1:57
	ds_read2_b32 v[106:107], v91 offset0:90 offset1:123
	ds_read2_b32 v[108:109], v91 offset0:156 offset1:189
	ds_read2_b32 v[112:113], v91 offset0:222 offset1:255
	v_add_lshl_u32 v89, v114, v89, 1
	v_and_b32_e32 v89, 0xffffff00, v89
	v_or3_b32 v114, v103, v89, v97
	v_ashrrev_i32_e32 v115, 31, v114
	s_waitcnt lgkmcnt(3)
	v_cvt_pk_bf16_f32 v104, v104, v105
	s_waitcnt lgkmcnt(2)
	v_cvt_pk_bf16_f32 v105, v106, v107
	s_waitcnt lgkmcnt(1)
	v_cvt_pk_bf16_f32 v106, v108, v109
	v_lshlrev_b64 v[108:109], 11, v[114:115]
	v_lshl_add_u64 v[108:109], v[76:77], 0, v[108:109]
	v_lshl_add_u64 v[108:109], v[108:109], 0, v[110:111]
	s_waitcnt lgkmcnt(0)
	v_cvt_pk_bf16_f32 v107, v112, v113
	v_lshl_add_u64 v[108:109], v[108:109], 0, v[68:69]
	global_store_dwordx4 v[108:109], v[104:107], off nt
	s_nop 1
	s_waitcnt lgkmcnt(0)
	s_and_b64 s[38:39], vcc, exec

.LBB0_337:
	s_or_b64 exec, exec, s[38:39]
	s_mov_b32 s6, 0x2e8ba2e9
	v_lshl_add_u64 v[58:59], v[32:33], 0, s[46:47]
	v_mul_hi_i32 v32, v101, s6
	v_lshrrev_b32_e32 v33, 31, v32
	v_ashrrev_i32_e32 v32, 5, v32
	v_add_u32_e32 v33, v32, v33
	s_movk_i32 s6, 0xb0
	v_mul_lo_u32 v32, v33, s6
	v_sub_u32_e32 v32, v101, v32
	v_lshlrev_b32_e32 v32, 5, v32
	v_lshl_or_b32 v102, v33, 6, v81
	v_ashrrev_i32_e32 v33, 31, v32
	s_movk_i32 s6, 0x5800
	v_mad_i64_i32 v[34:35], s[20:21], v102, s6, v[58:59]
	v_lshlrev_b64 v[60:61], 2, v[32:33]
	v_lshl_add_u64 v[32:33], v[34:35], 0, v[60:61]
	v_or_b32_e32 v34, 8, v102
	v_or_b32_e32 v40, 16, v102
	v_or_b32_e32 v42, 24, v102
	v_or_b32_e32 v50, 32, v102
	v_or_b32_e32 v52, 40, v102
	v_or_b32_e32 v62, 48, v102
	v_or_b32_e32 v64, 56, v102
	v_mad_i64_i32 v[34:35], s[20:21], v34, s6, v[58:59]
	v_mad_i64_i32 v[40:41], s[20:21], v40, s6, v[58:59]
	v_mad_i64_i32 v[42:43], s[20:21], v42, s6, v[58:59]
	v_mad_i64_i32 v[50:51], s[20:21], v50, s6, v[58:59]
	v_mad_i64_i32 v[52:53], s[20:21], v52, s6, v[58:59]
	v_mad_i64_i32 v[62:63], s[20:21], v62, s6, v[58:59]
	v_mad_i64_i32 v[58:59], s[20:21], v64, s6, v[58:59]
	v_lshl_add_u64 v[34:35], v[34:35], 0, v[60:61]
	v_lshl_add_u64 v[40:41], v[40:41], 0, v[60:61]
	v_lshl_add_u64 v[42:43], v[42:43], 0, v[60:61]
	v_lshl_add_u64 v[50:51], v[50:51], 0, v[60:61]
	v_lshl_add_u64 v[52:53], v[52:53], 0, v[60:61]
	v_lshl_add_u64 v[62:63], v[62:63], 0, v[60:61]
	v_lshl_add_u64 v[58:59], v[58:59], 0, v[60:61]
	v_lshl_add_u64 v[32:33], v[32:33], 0, v[48:49]
	v_lshl_add_u64 v[36:37], v[34:35], 0, v[48:49]
	v_lshl_add_u64 v[40:41], v[40:41], 0, v[48:49]
	v_lshl_add_u64 v[44:45], v[42:43], 0, v[48:49]
	v_lshl_add_u64 v[50:51], v[50:51], 0, v[48:49]
	v_lshl_add_u64 v[54:55], v[52:53], 0, v[48:49]
	v_lshl_add_u64 v[62:63], v[62:63], 0, v[48:49]
	v_lshl_add_u64 v[64:65], v[58:59], 0, v[48:49]
	global_load_dwordx4 v[32:35], v[32:33], off nt
	s_nop 0
	global_load_dwordx4 v[36:39], v[36:37], off nt
	s_nop 0
	global_load_dwordx4 v[40:43], v[40:41], off nt
	s_nop 0
	global_load_dwordx4 v[44:47], v[44:45], off nt
	s_nop 0
	global_load_dwordx4 v[50:53], v[50:51], off nt
	s_nop 0
	global_load_dwordx4 v[54:57], v[54:55], off nt
	s_nop 0
	global_load_dwordx4 v[58:61], v[62:63], off nt
	s_nop 0
	global_load_dwordx4 v[62:65], v[64:65], off nt
	v_lshl_add_u64 v[104:105], s[24:25], 2, v[88:89]
	v_ashrrev_i32_e32 v103, 31, v102
	v_cmp_ne_u64_e64 s[38:39], 0, v[88:89]
	v_mov_b32_e32 v88, 1.0
	v_lshl_add_u64 v[104:105], v[102:103], 2, v[104:105]
	v_mov_b32_e32 v90, 1.0
	v_mov_b32_e32 v92, 1.0
	s_and_saveexec_b64 s[54:55], s[38:39]
	s_cbranch_execz .LBB0_339
	global_load_dword v90, v[104:105], off
	global_load_dword v92, v[104:105], off offset:32

.LBB0_346:
	s_or_b64 exec, exec, s[52:53]
	s_mov_b32 s6, 0x2e8ba2e9
	v_mul_hi_i32 v69, v79, s6
	s_waitcnt vmcnt(1)
	v_pk_mul_f32 v[106:107], v[72:73], v[0:1] op_sel_hi:[0,1]
	v_lshrrev_b32_e32 v89, 31, v69
	v_ashrrev_i32_e32 v69, 5, v69
	ds_write2_b32 v99, v106, v107 offset1:1
	v_pk_mul_f32 v[106:107], v[72:73], v[2:3] op_sel_hi:[0,1]
	v_add_u32_e32 v69, v69, v89
	ds_write2_b32 v99, v106, v107 offset0:2 offset1:3
	s_waitcnt vmcnt(0)
	v_pk_mul_f32 v[106:107], v[74:75], v[4:5] op_sel_hi:[0,1]
	v_add_u32_e32 v89, 0x420, v99
	ds_write2_b32 v89, v106, v107 offset1:1
	v_pk_mul_f32 v[106:107], v[74:75], v[6:7] op_sel_hi:[0,1]
	v_add_u32_e32 v103, 0x428, v99
	ds_write2_b32 v103, v106, v107 offset1:1
	v_pk_mul_f32 v[108:109], v[70:71], v[8:9] op_sel_hi:[0,1]
	v_add_u32_e32 v106, 0x840, v99
	ds_write2_b32 v106, v108, v109 offset1:1
	v_pk_mul_f32 v[108:109], v[70:71], v[10:11] op_sel_hi:[0,1]
	v_add_u32_e32 v107, 0x848, v99
	ds_write2_b32 v107, v108, v109 offset1:1
	v_pk_mul_f32 v[110:111], v[78:79], v[12:13] op_sel_hi:[0,1]
	v_add_u32_e32 v108, 0xc60, v99
	ds_write2_b32 v108, v110, v111 offset1:1
	v_pk_mul_f32 v[110:111], v[78:79], v[14:15] op_sel_hi:[0,1]
	v_add_u32_e32 v109, 0xc68, v99
	ds_write2_b32 v109, v110, v111 offset1:1
	v_pk_mul_f32 v[112:113], v[82:83], v[16:17] op_sel_hi:[0,1]
	v_add_u32_e32 v110, 0x1080, v99
	ds_write2_b32 v110, v112, v113 offset1:1
	v_pk_mul_f32 v[112:113], v[82:83], v[18:19] op_sel_hi:[0,1]
	v_add_u32_e32 v111, 0x1088, v99
	ds_write2_b32 v111, v112, v113 offset1:1
	v_pk_mul_f32 v[114:115], v[84:85], v[20:21] op_sel_hi:[0,1]
	v_add_u32_e32 v112, 0x14a0, v99
	ds_write2_b32 v112, v114, v115 offset1:1
	v_pk_mul_f32 v[114:115], v[84:85], v[22:23] op_sel_hi:[0,1]
	v_add_u32_e32 v113, 0x14a8, v99
	ds_write2_b32 v113, v114, v115 offset1:1
	v_pk_mul_f32 v[116:117], v[80:81], v[24:25] op_sel_hi:[0,1]
	v_add_u32_e32 v114, 0x18c0, v99
	ds_write2_b32 v114, v116, v117 offset1:1
	v_pk_mul_f32 v[116:117], v[80:81], v[26:27] op_sel_hi:[0,1]
	v_add_u32_e32 v115, 0x18c8, v99
	ds_write2_b32 v115, v116, v117 offset1:1
	v_pk_mul_f32 v[120:121], v[86:87], v[28:29] op_sel_hi:[0,1]
	v_add_u32_e32 v116, 0x1ce0, v99
	ds_write2_b32 v116, v120, v121 offset1:1
	v_pk_mul_f32 v[120:121], v[86:87], v[30:31] op_sel_hi:[0,1]
	v_add_u32_e32 v117, 0x1ce8, v99
	ds_write2_b32 v117, v120, v121 offset1:1
	s_movk_i32 s6, 0xb0
	v_lshlrev_b32_e32 v104, 6, v69
	v_mul_lo_u32 v69, v69, s6
	s_waitcnt lgkmcnt(0)
	v_sub_u32_e32 v69, v79, v69
	ds_read2_b32 v[120:121], v91 offset1:33
	ds_read2_b32 v[122:123], v91 offset0:66 offset1:99
	ds_read2_b32 v[124:125], v91 offset0:132 offset1:165
	ds_read2_b32 v[126:127], v91 offset0:198 offset1:231
	v_lshlrev_b32_e32 v119, 5, v69
	v_or_b32_e32 v69, v119, v81
	s_movk_i32 s6, 0xaff
	v_cmp_lt_i32_e64 s[38:39], s6, v69
	s_waitcnt lgkmcnt(3)
	v_cvt_pk_bf16_f32 v120, v120, v121
	s_waitcnt lgkmcnt(2)
	v_cvt_pk_bf16_f32 v121, v122, v123
	s_waitcnt lgkmcnt(1)
	v_cvt_pk_bf16_f32 v122, v124, v125
	v_cndmask_b32_e64 v125, 0, v208, s[38:39]
	v_and_b32_e32 v128, 0x60, v119
	v_cndmask_b32_e64 v124, 0, 16, s[38:39]
	v_add_lshl_u32 v69, v125, v69, 1
	v_or_b32_e32 v124, v128, v124
	v_and_b32_e32 v69, 0xffffff00, v69
	v_or3_b32 v124, v124, v69, v87
	v_ashrrev_i32_e32 v125, 31, v124
	v_ashrrev_i32_e32 v105, 31, v104
	v_lshlrev_b64 v[124:125], 11, v[124:125]
	v_lshl_add_u64 v[124:125], v[66:67], 0, v[124:125]
	v_lshlrev_b64 v[104:105], 1, v[104:105]
	v_lshl_add_u64 v[124:125], v[124:125], 0, v[104:105]
	v_mov_b32_e32 v69, v49
	s_waitcnt lgkmcnt(0)
	v_cvt_pk_bf16_f32 v123, v126, v127
	v_lshl_add_u64 v[124:125], v[124:125], 0, v[68:69]
	global_store_dwordx4 v[124:125], v[120:123], off nt
	s_nop 1
	ds_read2_b32 v[120:121], v91 offset0:8 offset1:41
	ds_read2_b32 v[122:123], v91 offset0:74 offset1:107
	ds_read2_b32 v[124:125], v91 offset0:140 offset1:173
	ds_read2_b32 v[126:127], v91 offset0:206 offset1:239
	s_waitcnt lgkmcnt(3)
	v_cvt_pk_bf16_f32 v120, v120, v121
	s_waitcnt lgkmcnt(2)
	v_cvt_pk_bf16_f32 v121, v122, v123
	s_waitcnt lgkmcnt(1)
	v_cvt_pk_bf16_f32 v122, v124, v125
	v_or_b32_e32 v124, v119, v75
	v_cmp_lt_i32_e64 s[38:39], s6, v124
	s_waitcnt lgkmcnt(0)
	v_cvt_pk_bf16_f32 v123, v126, v127
	v_cndmask_b32_e64 v126, 0, v208, s[38:39]
	v_cndmask_b32_e64 v125, 0, 16, s[38:39]
	v_add_lshl_u32 v124, v126, v124, 1
	v_or_b32_e32 v125, v128, v125
	v_and_b32_e32 v124, 0xffffff00, v124
	v_or3_b32 v124, v125, v124, v93
	v_ashrrev_i32_e32 v125, 31, v124
	v_lshlrev_b64 v[124:125], 11, v[124:125]
	v_lshl_add_u64 v[124:125], v[66:67], 0, v[124:125]
	v_lshl_add_u64 v[124:125], v[124:125], 0, v[104:105]
	v_lshl_add_u64 v[124:125], v[124:125], 0, v[68:69]
	global_store_dwordx4 v[124:125], v[120:123], off nt
	s_nop 1
	ds_read2_b32 v[120:121], v91 offset0:16 offset1:49
	ds_read2_b32 v[122:123], v91 offset0:82 offset1:115
	ds_read2_b32 v[124:125], v91 offset0:148 offset1:181
	ds_read2_b32 v[126:127], v91 offset0:214 offset1:247
	s_waitcnt lgkmcnt(3)
	v_cvt_pk_bf16_f32 v120, v120, v121
	s_waitcnt lgkmcnt(2)
	v_cvt_pk_bf16_f32 v121, v122, v123
	s_waitcnt lgkmcnt(1)
	v_cvt_pk_bf16_f32 v122, v124, v125
	v_or_b32_e32 v124, v119, v83
	v_cmp_lt_i32_e64 s[38:39], s6, v124
	s_waitcnt lgkmcnt(0)
	v_cvt_pk_bf16_f32 v123, v126, v127
	v_or_b32_e32 v119, v119, v85
	v_cndmask_b32_e64 v126, 0, v208, s[38:39]
	v_cndmask_b32_e64 v125, 0, 16, s[38:39]
	v_add_lshl_u32 v124, v126, v124, 1
	v_or_b32_e32 v125, v128, v125
	v_and_b32_e32 v124, 0xffffff00, v124
	v_or3_b32 v124, v125, v124, v95
	v_ashrrev_i32_e32 v125, 31, v124
	v_lshlrev_b64 v[124:125], 11, v[124:125]
	v_lshl_add_u64 v[124:125], v[66:67], 0, v[124:125]
	v_cmp_lt_i32_e64 s[38:39], s6, v119
	v_lshl_add_u64 v[124:125], v[124:125], 0, v[104:105]
	v_lshl_add_u64 v[124:125], v[124:125], 0, v[68:69]
	v_cndmask_b32_e64 v129, 0, 16, s[38:39]
	global_store_dwordx4 v[124:125], v[120:123], off nt
	s_nop 1
	v_or_b32_e32 v128, v128, v129
	v_cndmask_b32_e64 v129, 0, v208, s[38:39]
	ds_read2_b32 v[120:121], v91 offset0:24 offset1:57
	ds_read2_b32 v[122:123], v91 offset0:90 offset1:123
	ds_read2_b32 v[124:125], v91 offset0:156 offset1:189
	ds_read2_b32 v[126:127], v91 offset0:222 offset1:255
	v_add_lshl_u32 v119, v129, v119, 1
	v_and_b32_e32 v119, 0xffffff00, v119
	v_or3_b32 v128, v128, v119, v97
	v_ashrrev_i32_e32 v129, 31, v128
	s_waitcnt lgkmcnt(3)
	v_cvt_pk_bf16_f32 v120, v120, v121
	s_waitcnt lgkmcnt(2)
	v_cvt_pk_bf16_f32 v121, v122, v123
	s_waitcnt lgkmcnt(1)
	v_cvt_pk_bf16_f32 v122, v124, v125
	v_lshlrev_b64 v[124:125], 11, v[128:129]
	v_lshl_add_u64 v[124:125], v[66:67], 0, v[124:125]
	v_lshl_add_u64 v[104:105], v[124:125], 0, v[104:105]
	s_waitcnt lgkmcnt(0)
	v_cvt_pk_bf16_f32 v123, v126, v127
	v_lshl_add_u64 v[104:105], v[104:105], 0, v[68:69]
	global_store_dwordx4 v[104:105], v[120:123], off nt
	s_nop 1
	s_waitcnt lgkmcnt(0)
	s_mov_b64 s[38:39], 0
	s_and_saveexec_b64 s[52:53], vcc
	s_cbranch_execz .LBB0_331
	v_add_u32_e32 v69, s70, v118
	v_cmp_gt_i32_e32 vcc, s33, v69
	s_and_saveexec_b64 s[54:55], vcc
	s_cbranch_execz .LBB0_330
	v_cmp_lt_i32_e64 s[38:39], s6, v69
	s_and_saveexec_b64 s[20:21], s[38:39]
	s_xor_b64 s[38:39], exec, s[20:21]
	s_cbranch_execz .LBB0_350
	s_load_dwordx2 s[56:57], s[0:1], 48
	s_waitcnt lgkmcnt(0)
	s_load_dwordx2 s[58:59], s[0:1], 40
	s_waitcnt lgkmcnt(0)
	v_add_u32_e32 v79, 0xfffff500, v69

.LBB0_352:
	s_or_b64 exec, exec, s[38:39]
	s_mov_b32 s6, 0x2e8ba2e9
	v_lshl_add_u64 v[24:25], v[0:1], 0, s[46:47]
	v_mul_hi_i32 v0, v79, s6
	v_lshrrev_b32_e32 v1, 31, v0
	v_ashrrev_i32_e32 v0, 5, v0
	v_add_u32_e32 v1, v0, v1
	s_movk_i32 s6, 0xb0
	v_mul_lo_u32 v0, v1, s6
	v_sub_u32_e32 v0, v79, v0
	v_lshlrev_b32_e32 v0, 5, v0
	v_lshl_or_b32 v104, v1, 6, v81
	v_ashrrev_i32_e32 v1, 31, v0
	s_movk_i32 s6, 0x5800
	v_mad_i64_i32 v[2:3], s[20:21], v104, s6, v[24:25]
	v_lshlrev_b64 v[26:27], 2, v[0:1]
	v_lshl_add_u64 v[0:1], v[2:3], 0, v[26:27]
	v_or_b32_e32 v2, 8, v104
	v_or_b32_e32 v8, 16, v104
	v_or_b32_e32 v10, 24, v104
	v_or_b32_e32 v16, 32, v104
	v_or_b32_e32 v18, 40, v104
	v_or_b32_e32 v28, 48, v104
	v_or_b32_e32 v30, 56, v104
	v_mad_i64_i32 v[2:3], s[20:21], v2, s6, v[24:25]
	v_mad_i64_i32 v[8:9], s[20:21], v8, s6, v[24:25]
	v_mad_i64_i32 v[10:11], s[20:21], v10, s6, v[24:25]
	v_mad_i64_i32 v[16:17], s[20:21], v16, s6, v[24:25]
	v_mad_i64_i32 v[18:19], s[20:21], v18, s6, v[24:25]
	v_mad_i64_i32 v[28:29], s[20:21], v28, s6, v[24:25]
	v_mad_i64_i32 v[24:25], s[20:21], v30, s6, v[24:25]
	v_lshl_add_u64 v[2:3], v[2:3], 0, v[26:27]
	v_lshl_add_u64 v[8:9], v[8:9], 0, v[26:27]
	v_lshl_add_u64 v[10:11], v[10:11], 0, v[26:27]
	v_lshl_add_u64 v[16:17], v[16:17], 0, v[26:27]
	v_lshl_add_u64 v[18:19], v[18:19], 0, v[26:27]
	v_lshl_add_u64 v[28:29], v[28:29], 0, v[26:27]
	v_lshl_add_u64 v[24:25], v[24:25], 0, v[26:27]
	v_lshl_add_u64 v[0:1], v[0:1], 0, v[48:49]
	v_lshl_add_u64 v[4:5], v[2:3], 0, v[48:49]
	v_lshl_add_u64 v[8:9], v[8:9], 0, v[48:49]
	v_lshl_add_u64 v[12:13], v[10:11], 0, v[48:49]
	v_lshl_add_u64 v[16:17], v[16:17], 0, v[48:49]
	v_lshl_add_u64 v[20:21], v[18:19], 0, v[48:49]
	v_lshl_add_u64 v[28:29], v[28:29], 0, v[48:49]
	v_lshl_add_u64 v[30:31], v[24:25], 0, v[48:49]
	global_load_dwordx4 v[0:3], v[0:1], off nt
	s_nop 0
	global_load_dwordx4 v[4:7], v[4:5], off nt
	s_nop 0
	global_load_dwordx4 v[8:11], v[8:9], off nt
	s_nop 0
	global_load_dwordx4 v[12:15], v[12:13], off nt
	s_nop 0
	global_load_dwordx4 v[16:19], v[16:17], off nt
	s_nop 0
	global_load_dwordx4 v[20:23], v[20:21], off nt
	s_nop 0
	global_load_dwordx4 v[24:27], v[28:29], off nt
	s_nop 0
	global_load_dwordx4 v[28:31], v[30:31], off nt
	v_lshl_add_u64 v[118:119], s[24:25], 2, v[70:71]
	v_ashrrev_i32_e32 v105, 31, v104
	v_cmp_ne_u64_e64 s[38:39], 0, v[70:71]
	v_mov_b32_e32 v70, 1.0
	v_lshl_add_u64 v[104:105], v[104:105], 2, v[118:119]
	v_mov_b32_e32 v72, 1.0
	v_mov_b32_e32 v74, 1.0
	s_and_saveexec_b64 s[56:57], s[38:39]
	s_cbranch_execz .LBB0_354
	global_load_dword v72, v[104:105], off
	global_load_dword v74, v[104:105], off offset:32

.LBB0_363:
	s_waitcnt vmcnt(5)
	v_ashrrev_i32_e32 v8, 31, v7
	v_lshrrev_b32_e32 v8, 25, v8
	v_add_u32_e32 v8, v7, v8
	v_ashrrev_i32_e32 v8, 7, v8
	v_ashrrev_i32_e32 v9, 31, v8
	v_lshlrev_b32_e32 v10, 11, v8
	v_lshlrev_b64 v[8:9], 11, v[8:9]
	v_sub_u32_e32 v10, v6, v10
	v_lshl_add_u64 v[8:9], s[44:45], 0, v[8:9]
	v_ashrrev_i32_e32 v11, 31, v10
	v_add_u32_e32 v7, s18, v7
	v_lshl_add_u64 v[8:9], v[8:9], 0, v[10:11]
	global_store_dwordx4 v[8:9], v[0:3], off nt
	s_nop 1
	v_cmp_lt_i32_e64 s[38:39], s81, v7
	s_or_b64 s[46:47], s[38:39], s[46:47]
	v_add_u32_e32 v6, s6, v6
	s_andn2_b64 exec, exec, s[46:47]
	s_cbranch_execnz .LBB0_363

.LBB0_366:
	s_waitcnt vmcnt(5)
	v_ashrrev_i32_e32 v10, 31, v7
	v_lshrrev_b32_e32 v10, 28, v10
	v_add_u32_e32 v10, v7, v10
	v_mov_b64_e32 v[8:9], s[42:43]
	v_ashrrev_i32_e32 v10, 4, v10
	v_mad_i64_i32 v[8:9], s[8:9], v10, s95, v[8:9]
	v_lshlrev_b32_e32 v10, 8, v10
	v_sub_u32_e32 v10, v6, v10
	v_ashrrev_i32_e32 v11, 31, v10
	v_add_u32_e32 v7, s18, v7
	v_lshl_add_u64 v[8:9], v[8:9], 0, v[10:11]
	global_store_dwordx4 v[8:9], v[0:3], off nt
	s_nop 1
	v_cmp_lt_i32_e32 vcc, s81, v7
	s_or_b64 s[44:45], vcc, s[44:45]
	v_add_u32_e32 v6, s6, v6
	s_andn2_b64 exec, exec, s[44:45]
	s_cbranch_execnz .LBB0_366

.LBB0_369:
	s_waitcnt vmcnt(5)
	v_ashrrev_i32_e32 v8, 31, v4
	v_lshrrev_b32_e32 v8, 27, v8
	v_add_u32_e32 v8, v4, v8
	v_mov_b64_e32 v[6:7], s[40:41]
	v_ashrrev_i32_e32 v8, 5, v8
	v_mad_i64_i32 v[6:7], s[8:9], v8, s95, v[6:7]
	v_lshlrev_b32_e32 v8, 9, v8
	v_sub_u32_e32 v8, v5, v8
	v_ashrrev_i32_e32 v9, 31, v8
	v_add_u32_e32 v4, s18, v4
	v_lshl_add_u64 v[6:7], v[6:7], 0, v[8:9]
	global_store_dwordx4 v[6:7], v[0:3], off nt
	s_nop 1
	v_cmp_lt_i32_e32 vcc, s84, v4
	s_or_b64 s[42:43], vcc, s[42:43]
	v_add_u32_e32 v5, s6, v5
	s_andn2_b64 exec, exec, s[42:43]
	s_cbranch_execnz .LBB0_369

.LBB0_1473:
	s_lshr_b32 s6, s66, 5
	v_cvt_f32_u32_e32 v0, s6
	s_sub_i32 s21, 0, s6
	s_abs_i32 s20, s57
	s_ashr_i32 s18, s57, 31
	v_rcp_iflag_f32_e32 v0, v0
	v_lshrrev_b32_e32 v71, 3, v69
	v_lshlrev_b32_e32 v1, 2, v69
	v_and_b32_e32 v2, 28, v1
	v_mul_f32_e32 v0, 0x4f7ffffe, v0
	v_cvt_u32_f32_e32 v0, v0
	v_lshlrev_b32_e32 v48, 2, v2
	s_waitcnt vmcnt(1)
	v_mov_b32_e32 v68, 1.0
	v_mov_b32_e32 v70, 1.0
	v_readfirstlane_b32 s26, v0
	s_mul_i32 s21, s21, s26
	s_mul_hi_u32 s21, s26, s21
	s_add_i32 s26, s26, s21
	s_mul_hi_u32 s21, s20, s26
	s_mul_i32 s26, s21, s6
	s_sub_i32 s20, s20, s26
	s_add_i32 s27, s21, 1
	s_sub_i32 s26, s20, s6
	s_cmp_ge_u32 s20, s6
	s_cselect_b32 s21, s27, s21
	s_cselect_b32 s20, s26, s20
	s_add_i32 s26, s21, 1
	s_cmp_ge_u32 s20, s6
	s_cselect_b32 s20, s26, s21
	s_xor_b32 s20, s20, s18
	s_sub_i32 s18, s20, s18
	s_mul_i32 s6, s18, s6
	s_waitcnt vmcnt(0)
	v_lshl_or_b32 v32, s18, 6, v71
	s_sub_i32 s6, s57, s6
	v_ashrrev_i32_e32 v33, 31, v32
	v_or_b32_e32 v2, 8, v32
	v_or_b32_e32 v8, 16, v32
	v_or_b32_e32 v10, 24, v32
	v_or_b32_e32 v16, 32, v32
	v_or_b32_e32 v18, 40, v32
	v_or_b32_e32 v24, 48, v32
	v_or_b32_e32 v26, 56, v32
	s_lshl_b32 s20, s6, 5
	v_mul_lo_u32 v28, v33, s66
	v_mad_u64_u32 v[0:1], s[26:27], v32, s66, 0
	v_mad_u64_u32 v[2:3], s[26:27], v2, s66, 0
	v_mad_u64_u32 v[8:9], s[26:27], v8, s66, 0
	v_mad_u64_u32 v[10:11], s[26:27], v10, s66, 0
	v_mad_u64_u32 v[16:17], s[26:27], v16, s66, 0
	v_mad_u64_u32 v[18:19], s[26:27], v18, s66, 0
	v_mad_u64_u32 v[24:25], s[26:27], v24, s66, 0
	v_mad_u64_u32 v[26:27], s[26:27], v26, s66, 0
	s_ashr_i32 s21, s20, 31
	v_add_u32_e32 v1, v1, v28
	v_add_u32_e32 v3, v3, v28
	v_add_u32_e32 v9, v9, v28
	v_add_u32_e32 v11, v11, v28
	v_add_u32_e32 v17, v17, v28
	v_add_u32_e32 v19, v19, v28
	v_add_u32_e32 v25, v25, v28
	v_add_u32_e32 v27, v27, v28
	v_lshl_add_u64 v[0:1], v[0:1], 2, s[38:39]
	s_lshl_b64 s[20:21], s[20:21], 2
	v_lshl_add_u64 v[2:3], v[2:3], 2, s[38:39]
	v_lshl_add_u64 v[8:9], v[8:9], 2, s[38:39]
	v_lshl_add_u64 v[10:11], v[10:11], 2, s[38:39]
	v_lshl_add_u64 v[16:17], v[16:17], 2, s[38:39]
	v_lshl_add_u64 v[18:19], v[18:19], 2, s[38:39]
	v_lshl_add_u64 v[24:25], v[24:25], 2, s[38:39]
	v_lshl_add_u64 v[26:27], v[26:27], 2, s[38:39]
	v_lshl_add_u64 v[0:1], v[0:1], 0, s[20:21]
	v_lshl_add_u64 v[2:3], v[2:3], 0, s[20:21]
	v_lshl_add_u64 v[8:9], v[8:9], 0, s[20:21]
	v_lshl_add_u64 v[10:11], v[10:11], 0, s[20:21]
	v_lshl_add_u64 v[16:17], v[16:17], 0, s[20:21]
	v_lshl_add_u64 v[18:19], v[18:19], 0, s[20:21]
	v_lshl_add_u64 v[24:25], v[24:25], 0, s[20:21]
	v_lshl_add_u64 v[26:27], v[26:27], 0, s[20:21]
	v_lshl_add_u64 v[0:1], v[0:1], 0, v[48:49]
	v_lshl_add_u64 v[4:5], v[2:3], 0, v[48:49]
	v_lshl_add_u64 v[8:9], v[8:9], 0, v[48:49]
	v_lshl_add_u64 v[12:13], v[10:11], 0, v[48:49]
	v_lshl_add_u64 v[16:17], v[16:17], 0, v[48:49]
	v_lshl_add_u64 v[20:21], v[18:19], 0, v[48:49]
	v_lshl_add_u64 v[24:25], v[24:25], 0, v[48:49]
	v_lshl_add_u64 v[28:29], v[26:27], 0, v[48:49]
	global_load_dwordx4 v[0:3], v[0:1], off nt
	s_nop 0
	global_load_dwordx4 v[4:7], v[4:5], off nt
	s_nop 0
	global_load_dwordx4 v[8:11], v[8:9], off nt
	s_nop 0
	global_load_dwordx4 v[12:15], v[12:13], off nt
	s_nop 0
	global_load_dwordx4 v[16:19], v[16:17], off nt
	s_nop 0
	global_load_dwordx4 v[20:23], v[20:21], off nt
	s_nop 0
	global_load_dwordx4 v[24:27], v[24:25], off nt
	s_nop 0
	global_load_dwordx4 v[28:31], v[28:29], off nt
	s_cmp_lg_u64 s[40:41], 0
	s_cselect_b64 s[42:43], -1, 0
	s_cmp_eq_u64 s[40:41], 0
	v_lshl_add_u64 v[32:33], v[32:33], 2, s[40:41]
	v_mov_b32_e32 v72, 1.0
	s_cbranch_scc1 .LBB0_1475
	global_load_dword v70, v[32:33], off
	global_load_dword v72, v[32:33], off offset:32

.LBB0_1483:
	s_waitcnt lgkmcnt(3)
	v_cvt_pk_bf16_f32 v102, v102, v103
	s_waitcnt lgkmcnt(2)
	v_cvt_pk_bf16_f32 v103, v104, v105
	s_waitcnt lgkmcnt(1)
	v_cvt_pk_bf16_f32 v104, v106, v107
	v_mad_u64_u32 v[106:107], s[20:21], v91, s65, 0
	s_waitcnt lgkmcnt(0)
	v_cvt_pk_bf16_f32 v105, v108, v109
	v_ashrrev_i32_e32 v93, 31, v91
	v_mov_b32_e32 v108, v107
	v_mad_u64_u32 v[108:109], s[20:21], v93, s65, v[108:109]
	v_mov_b32_e32 v107, v108
	v_lshl_add_u64 v[106:107], v[106:107], 1, s[42:43]
	v_lshl_add_u64 v[106:107], s[46:47], 1, v[106:107]
	v_lshl_add_u64 v[106:107], s[88:89], 1, v[106:107]
	v_mov_b32_e32 v101, v49
	v_lshl_add_u64 v[100:101], v[106:107], 0, v[100:101]
	global_store_dwordx4 v[100:101], v[102:105], off nt
	s_nop 1
	s_waitcnt lgkmcnt(0)
	s_and_b64 s[20:21], s[86:87], exec
	s_cselect_b32 s64, s18, s64

.LBB0_1534:
	s_lshr_b32 s6, s53, 5
	v_cvt_f32_u32_e32 v32, s6
	s_sub_i32 s26, 0, s6
	s_abs_i32 s21, s56
	s_ashr_i32 s20, s56, 31
	v_rcp_iflag_f32_e32 v32, v32
	v_mov_b32_e32 v84, 1.0
	v_mov_b32_e32 v86, 1.0
	v_mov_b32_e32 v88, 1.0
	v_mul_f32_e32 v32, 0x4f7ffffe, v32
	v_cvt_u32_f32_e32 v32, v32
	s_nop 0
	v_readfirstlane_b32 s27, v32
	s_mul_i32 s26, s26, s27
	s_mul_hi_u32 s26, s27, s26
	s_add_i32 s27, s27, s26
	s_mul_hi_u32 s26, s21, s27
	s_mul_i32 s27, s26, s6
	s_sub_i32 s21, s21, s27
	s_add_i32 s33, s26, 1
	s_sub_i32 s27, s21, s6
	s_cmp_ge_u32 s21, s6
	s_cselect_b32 s26, s33, s26
	s_cselect_b32 s21, s27, s21
	s_add_i32 s27, s26, 1
	s_cmp_ge_u32 s21, s6
	s_cselect_b32 s21, s27, s26
	s_xor_b32 s21, s21, s20
	s_sub_i32 s20, s21, s20
	s_mul_i32 s6, s20, s6
	v_lshl_or_b32 v90, s20, 6, v71
	s_sub_i32 s6, s56, s6
	v_ashrrev_i32_e32 v91, 31, v90
	v_or_b32_e32 v34, 8, v90
	v_or_b32_e32 v40, 16, v90
	v_or_b32_e32 v42, 24, v90
	v_or_b32_e32 v50, 32, v90
	v_or_b32_e32 v52, 40, v90
	v_or_b32_e32 v58, 48, v90
	v_or_b32_e32 v60, 56, v90
	s_lshl_b32 s20, s6, 5
	v_mul_lo_u32 v62, v91, s53
	v_mad_u64_u32 v[32:33], s[26:27], v90, s53, 0
	v_mad_u64_u32 v[34:35], s[26:27], v34, s53, 0
	v_mad_u64_u32 v[40:41], s[26:27], v40, s53, 0
	v_mad_u64_u32 v[42:43], s[26:27], v42, s53, 0
	v_mad_u64_u32 v[50:51], s[26:27], v50, s53, 0
	v_mad_u64_u32 v[52:53], s[26:27], v52, s53, 0
	v_mad_u64_u32 v[58:59], s[26:27], v58, s53, 0
	v_mad_u64_u32 v[60:61], s[26:27], v60, s53, 0
	s_ashr_i32 s21, s20, 31
	v_add_u32_e32 v33, v33, v62
	v_add_u32_e32 v35, v35, v62
	v_add_u32_e32 v41, v41, v62
	v_add_u32_e32 v43, v43, v62
	v_add_u32_e32 v51, v51, v62
	v_add_u32_e32 v53, v53, v62
	v_add_u32_e32 v59, v59, v62
	v_add_u32_e32 v61, v61, v62
	v_lshl_add_u64 v[32:33], v[32:33], 2, s[38:39]
	s_lshl_b64 s[20:21], s[20:21], 2
	v_lshl_add_u64 v[34:35], v[34:35], 2, s[38:39]
	v_lshl_add_u64 v[40:41], v[40:41], 2, s[38:39]
	v_lshl_add_u64 v[42:43], v[42:43], 2, s[38:39]
	v_lshl_add_u64 v[50:51], v[50:51], 2, s[38:39]
	v_lshl_add_u64 v[52:53], v[52:53], 2, s[38:39]
	v_lshl_add_u64 v[58:59], v[58:59], 2, s[38:39]
	v_lshl_add_u64 v[60:61], v[60:61], 2, s[38:39]
	v_lshl_add_u64 v[32:33], v[32:33], 0, s[20:21]
	v_lshl_add_u64 v[34:35], v[34:35], 0, s[20:21]
	v_lshl_add_u64 v[40:41], v[40:41], 0, s[20:21]
	v_lshl_add_u64 v[42:43], v[42:43], 0, s[20:21]
	v_lshl_add_u64 v[50:51], v[50:51], 0, s[20:21]
	v_lshl_add_u64 v[52:53], v[52:53], 0, s[20:21]
	v_lshl_add_u64 v[58:59], v[58:59], 0, s[20:21]
	v_lshl_add_u64 v[60:61], v[60:61], 0, s[20:21]
	v_lshl_add_u64 v[32:33], v[32:33], 0, v[48:49]
	v_lshl_add_u64 v[36:37], v[34:35], 0, v[48:49]
	v_lshl_add_u64 v[40:41], v[40:41], 0, v[48:49]
	v_lshl_add_u64 v[44:45], v[42:43], 0, v[48:49]
	v_lshl_add_u64 v[50:51], v[50:51], 0, v[48:49]
	v_lshl_add_u64 v[54:55], v[52:53], 0, v[48:49]
	v_lshl_add_u64 v[58:59], v[58:59], 0, v[48:49]
	v_lshl_add_u64 v[62:63], v[60:61], 0, v[48:49]
	global_load_dwordx4 v[32:35], v[32:33], off nt
	s_nop 0
	global_load_dwordx4 v[36:39], v[36:37], off nt
	s_nop 0
	global_load_dwordx4 v[40:43], v[40:41], off nt
	s_nop 0
	global_load_dwordx4 v[44:47], v[44:45], off nt
	s_nop 0
	global_load_dwordx4 v[50:53], v[50:51], off nt
	s_nop 0
	global_load_dwordx4 v[54:57], v[54:55], off nt
	s_nop 0
	global_load_dwordx4 v[58:61], v[58:59], off nt
	s_nop 0
	global_load_dwordx4 v[62:65], v[62:63], off nt
	s_cmp_lg_u64 s[40:41], 0
	s_cselect_b64 s[88:89], -1, 0
	s_cmp_eq_u64 s[40:41], 0
	v_lshl_add_u64 v[100:101], v[90:91], 2, s[40:41]
	s_cbranch_scc1 .LBB0_1536
	global_load_dword v86, v[100:101], off
	global_load_dword v88, v[100:101], off offset:32

.LBB0_1548:
	s_waitcnt lgkmcnt(3)
	v_cvt_pk_bf16_f32 v120, v100, v101
	v_mad_u64_u32 v[100:101], s[20:21], v108, s52, 0
	s_waitcnt lgkmcnt(2)
	v_cvt_pk_bf16_f32 v121, v102, v103
	v_ashrrev_i32_e32 v103, 31, v108
	v_mov_b32_e32 v102, v101
	v_mad_u64_u32 v[102:103], s[20:21], v103, s52, v[102:103]
	v_mov_b32_e32 v101, v102
	s_lshl_b32 s88, s6, 6
	v_lshl_add_u64 v[100:101], v[100:101], 1, s[44:45]
	s_ashr_i32 s89, s88, 31
	v_lshl_add_u64 v[100:101], s[24:25], 1, v[100:101]
	v_lshl_add_u64 v[102:103], s[88:89], 1, v[100:101]
	v_lshlrev_b32_e32 v100, 1, v66
	v_mov_b32_e32 v101, v49
	s_waitcnt lgkmcnt(1)
	v_cvt_pk_bf16_f32 v122, v104, v105
	s_waitcnt lgkmcnt(0)
	v_cvt_pk_bf16_f32 v123, v106, v107
	v_lshl_add_u64 v[102:103], v[102:103], 0, v[100:101]
	global_store_dwordx4 v[102:103], v[120:123], off nt
	s_nop 1
	ds_read2_b32 v[102:103], v81 offset0:8 offset1:41
	ds_read2_b32 v[104:105], v81 offset0:74 offset1:107
	ds_read2_b32 v[106:107], v81 offset0:140 offset1:173
	ds_read2_b32 v[108:109], v81 offset0:206 offset1:239
	v_cndmask_b32_e64 v101, 0, 1, s[40:41]
	v_cmp_ne_u32_e64 s[38:39], 1, v101
	s_andn2_b64 vcc, exec, s[40:41]
	v_or_b32_e32 v101, s33, v73
	s_cbranch_vccnz .LBB0_1550
	s_movk_i32 s6, 0xaff
	v_cmp_lt_i32_e32 vcc, s6, v101
	s_and_b32 s6, s33, 0x60
	s_nop 0
	v_cndmask_b32_e32 v119, 0, v209, vcc
	v_add_lshl_u32 v101, v119, v101, 1
	v_cndmask_b32_e64 v119, 0, 16, vcc
	v_and_b32_e32 v101, 0xffffff00, v101
	v_or_b32_e32 v119, s6, v119
	v_or3_b32 v101, v119, v101, v83

.LBB0_1554:
	s_waitcnt lgkmcnt(3)
	v_cvt_pk_bf16_f32 v102, v102, v103
	s_waitcnt lgkmcnt(2)
	v_cvt_pk_bf16_f32 v103, v104, v105
	s_waitcnt lgkmcnt(1)
	v_cvt_pk_bf16_f32 v104, v106, v107
	v_mad_u64_u32 v[106:107], s[20:21], v101, s52, 0
	s_waitcnt lgkmcnt(0)
	v_cvt_pk_bf16_f32 v105, v108, v109
	v_ashrrev_i32_e32 v109, 31, v101
	v_mov_b32_e32 v108, v107
	v_mad_u64_u32 v[108:109], s[20:21], v109, s52, v[108:109]
	v_mov_b32_e32 v107, v108
	v_lshl_add_u64 v[106:107], v[106:107], 1, s[44:45]
	v_lshl_add_u64 v[106:107], s[24:25], 1, v[106:107]
	v_lshl_add_u64 v[106:107], s[88:89], 1, v[106:107]
	v_mov_b32_e32 v101, v49
	v_lshl_add_u64 v[106:107], v[106:107], 0, v[100:101]
	global_store_dwordx4 v[106:107], v[102:105], off nt
	s_nop 1
	ds_read2_b32 v[102:103], v81 offset0:16 offset1:49
	ds_read2_b32 v[104:105], v81 offset0:82 offset1:115
	ds_read2_b32 v[106:107], v81 offset0:148 offset1:181
	ds_read2_b32 v[108:109], v81 offset0:214 offset1:247
	s_and_b64 vcc, exec, s[38:39]
	v_or_b32_e32 v101, s33, v75
	s_cbranch_vccnz .LBB0_1556
	s_movk_i32 s6, 0xaff
	v_cmp_lt_i32_e32 vcc, s6, v101
	s_and_b32 s6, s33, 0x60
	s_nop 0
	v_cndmask_b32_e32 v119, 0, v209, vcc
	v_add_lshl_u32 v101, v119, v101, 1
	v_cndmask_b32_e64 v119, 0, 16, vcc
	v_and_b32_e32 v101, 0xffffff00, v101
	v_or_b32_e32 v119, s6, v119
	v_or3_b32 v101, v119, v101, v85

.LBB0_1560:
	s_waitcnt lgkmcnt(3)
	v_cvt_pk_bf16_f32 v102, v102, v103
	s_waitcnt lgkmcnt(2)
	v_cvt_pk_bf16_f32 v103, v104, v105
	s_waitcnt lgkmcnt(1)
	v_cvt_pk_bf16_f32 v104, v106, v107
	v_mad_u64_u32 v[106:107], s[20:21], v101, s52, 0
	s_waitcnt lgkmcnt(0)
	v_cvt_pk_bf16_f32 v105, v108, v109
	v_ashrrev_i32_e32 v109, 31, v101
	v_mov_b32_e32 v108, v107
	v_mad_u64_u32 v[108:109], s[20:21], v109, s52, v[108:109]
	v_mov_b32_e32 v107, v108
	v_lshl_add_u64 v[106:107], v[106:107], 1, s[44:45]
	v_lshl_add_u64 v[106:107], s[24:25], 1, v[106:107]
	v_lshl_add_u64 v[106:107], s[88:89], 1, v[106:107]
	v_mov_b32_e32 v101, v49
	v_lshl_add_u64 v[106:107], v[106:107], 0, v[100:101]
	global_store_dwordx4 v[106:107], v[102:105], off nt
	s_nop 1
	ds_read2_b32 v[102:103], v81 offset0:24 offset1:57
	ds_read2_b32 v[104:105], v81 offset0:90 offset1:123
	ds_read2_b32 v[106:107], v81 offset0:156 offset1:189
	ds_read2_b32 v[108:109], v81 offset0:222 offset1:255
	s_and_b64 vcc, exec, s[38:39]
	v_or_b32_e32 v101, s33, v77
	s_cbranch_vccnz .LBB0_1562
	s_movk_i32 s6, 0xaff
	v_cmp_lt_i32_e32 vcc, s6, v101
	s_and_b32 s6, s33, 0x60
	s_nop 0
	v_cndmask_b32_e32 v119, 0, v209, vcc
	v_add_lshl_u32 v101, v119, v101, 1
	v_cndmask_b32_e64 v119, 0, 16, vcc
	v_and_b32_e32 v101, 0xffffff00, v101
	v_or_b32_e32 v119, s6, v119
	v_or3_b32 v101, v119, v101, v87

.LBB0_1566:
	s_waitcnt lgkmcnt(3)
	v_cvt_pk_bf16_f32 v102, v102, v103
	s_waitcnt lgkmcnt(2)
	v_cvt_pk_bf16_f32 v103, v104, v105
	s_waitcnt lgkmcnt(1)
	v_cvt_pk_bf16_f32 v104, v106, v107
	v_mad_u64_u32 v[106:107], s[20:21], v101, s52, 0
	s_waitcnt lgkmcnt(0)
	v_cvt_pk_bf16_f32 v105, v108, v109
	v_ashrrev_i32_e32 v109, 31, v101
	v_mov_b32_e32 v108, v107
	v_mad_u64_u32 v[108:109], s[20:21], v109, s52, v[108:109]
	v_mov_b32_e32 v107, v108
	v_lshl_add_u64 v[106:107], v[106:107], 1, s[44:45]
	v_lshl_add_u64 v[106:107], s[24:25], 1, v[106:107]
	v_lshl_add_u64 v[106:107], s[88:89], 1, v[106:107]
	v_mov_b32_e32 v101, v49
	v_lshl_add_u64 v[106:107], v[106:107], 0, v[100:101]
	global_store_dwordx4 v[106:107], v[102:105], off nt
	s_nop 1
	s_waitcnt lgkmcnt(0)
	s_andn2_b64 vcc, exec, s[86:87]
	s_mov_b64 s[86:87], 0
	s_cbranch_vccnz .LBB0_1484
	v_readlane_b32 s6, v255, 4
	s_add_i32 s18, s18, s6
	s_cmp_lt_i32 s18, s93
	s_cselect_b64 s[86:87], -1, 0
	s_cmp_ge_i32 s18, s93
	s_cbranch_scc1 .LBB0_1625
	s_cmpk_gt_i32 s18, 0xaff
	s_mov_b64 s[88:89], -1
	s_cbranch_scc0 .LBB0_1615
	s_cmpk_gt_u32 s18, 0x15ff
	s_cbranch_scc0 .LBB0_1612
	s_cmpk_gt_u32 s18, 0x1b7f
	s_cbranch_scc0 .LBB0_1609
	s_cmpk_gt_u32 s18, 0x20ff
	s_cbranch_scc0 .LBB0_1606
	s_add_i32 s33, s18, 0xffffdf00
	s_cmp_ge_i32 s33, s92
	s_cbranch_scc0 .LBB0_1598
	s_sub_i32 s47, s33, s92
	s_cmpk_gt_i32 s47, 0x1ff
	s_cbranch_scc0 .LBB0_1591
	v_readlane_b32 s20, v255, 35
	v_readlane_b32 s21, v255, 36
	s_add_i32 s90, s47, 0xfffffe00
	s_mov_b64 s[40:41], -1
	s_and_b64 vcc, exec, s[20:21]
	s_cbranch_vccz .LBB0_1584
	s_cmpk_gt_u32 s47, 0x20f
	s_cbranch_scc0 .LBB0_1581
	s_cmpk_gt_u32 s47, 0x21f
	s_cbranch_scc0 .LBB0_1578
	s_add_i32 s57, s47, 0xfffffde0
	v_readlane_b32 s26, v255, 47
	s_load_dwordx2 s[20:21], s[0:1], 0x98
	s_waitcnt lgkmcnt(0)
	v_readlane_b32 s27, v255, 48
	s_add_u32 s38, s20, s26
	s_addc_u32 s39, s21, s27
	s_mov_b64 s[40:41], 0

.LBB0_1617:
	s_lshr_b32 s6, s66, 5
	v_cvt_f32_u32_e32 v0, s6
	s_sub_i32 s26, 0, s6
	s_abs_i32 s21, s57
	s_ashr_i32 s20, s57, 31
	v_rcp_iflag_f32_e32 v0, v0
	v_mov_b32_e32 v68, 1.0
	v_mov_b32_e32 v70, 1.0
	v_mov_b32_e32 v72, 1.0
	v_mul_f32_e32 v0, 0x4f7ffffe, v0
	v_cvt_u32_f32_e32 v0, v0
	s_nop 0
	v_readfirstlane_b32 s27, v0
	s_mul_i32 s26, s26, s27
	s_mul_hi_u32 s26, s27, s26
	s_add_i32 s27, s27, s26
	s_mul_hi_u32 s26, s21, s27
	s_mul_i32 s27, s26, s6
	s_sub_i32 s21, s21, s27
	s_add_i32 s33, s26, 1
	s_sub_i32 s27, s21, s6
	s_cmp_ge_u32 s21, s6
	s_cselect_b32 s26, s33, s26
	s_cselect_b32 s21, s27, s21
	s_add_i32 s27, s26, 1
	s_cmp_ge_u32 s21, s6
	s_cselect_b32 s21, s27, s26
	s_xor_b32 s21, s21, s20
	s_sub_i32 s20, s21, s20
	s_mul_i32 s6, s20, s6
	v_lshl_or_b32 v102, s20, 6, v71
	s_sub_i32 s6, s57, s6
	v_ashrrev_i32_e32 v103, 31, v102
	v_or_b32_e32 v2, 8, v102
	v_or_b32_e32 v8, 16, v102
	v_or_b32_e32 v10, 24, v102
	v_or_b32_e32 v16, 32, v102
	v_or_b32_e32 v18, 40, v102
	v_or_b32_e32 v24, 48, v102
	v_or_b32_e32 v26, 56, v102
	s_lshl_b32 s20, s6, 5
	v_mul_lo_u32 v28, v103, s66
	v_mad_u64_u32 v[0:1], s[26:27], v102, s66, 0
	v_mad_u64_u32 v[2:3], s[26:27], v2, s66, 0
	v_mad_u64_u32 v[8:9], s[26:27], v8, s66, 0
	v_mad_u64_u32 v[10:11], s[26:27], v10, s66, 0
	v_mad_u64_u32 v[16:17], s[26:27], v16, s66, 0
	v_mad_u64_u32 v[18:19], s[26:27], v18, s66, 0
	v_mad_u64_u32 v[24:25], s[26:27], v24, s66, 0
	v_mad_u64_u32 v[26:27], s[26:27], v26, s66, 0
	s_ashr_i32 s21, s20, 31
	v_add_u32_e32 v1, v1, v28
	v_add_u32_e32 v3, v3, v28
	v_add_u32_e32 v9, v9, v28
	v_add_u32_e32 v11, v11, v28
	v_add_u32_e32 v17, v17, v28
	v_add_u32_e32 v19, v19, v28
	v_add_u32_e32 v25, v25, v28
	v_add_u32_e32 v27, v27, v28
	v_lshl_add_u64 v[0:1], v[0:1], 2, s[38:39]
	s_lshl_b64 s[20:21], s[20:21], 2
	v_lshl_add_u64 v[2:3], v[2:3], 2, s[38:39]
	v_lshl_add_u64 v[8:9], v[8:9], 2, s[38:39]
	v_lshl_add_u64 v[10:11], v[10:11], 2, s[38:39]
	v_lshl_add_u64 v[16:17], v[16:17], 2, s[38:39]
	v_lshl_add_u64 v[18:19], v[18:19], 2, s[38:39]
	v_lshl_add_u64 v[24:25], v[24:25], 2, s[38:39]
	v_lshl_add_u64 v[26:27], v[26:27], 2, s[38:39]
	v_lshl_add_u64 v[0:1], v[0:1], 0, s[20:21]
	v_lshl_add_u64 v[2:3], v[2:3], 0, s[20:21]
	v_lshl_add_u64 v[8:9], v[8:9], 0, s[20:21]
	v_lshl_add_u64 v[10:11], v[10:11], 0, s[20:21]
	v_lshl_add_u64 v[16:17], v[16:17], 0, s[20:21]
	v_lshl_add_u64 v[18:19], v[18:19], 0, s[20:21]
	v_lshl_add_u64 v[24:25], v[24:25], 0, s[20:21]
	v_lshl_add_u64 v[26:27], v[26:27], 0, s[20:21]
	v_lshl_add_u64 v[0:1], v[0:1], 0, v[48:49]
	v_lshl_add_u64 v[4:5], v[2:3], 0, v[48:49]
	v_lshl_add_u64 v[8:9], v[8:9], 0, v[48:49]
	v_lshl_add_u64 v[12:13], v[10:11], 0, v[48:49]
	v_lshl_add_u64 v[16:17], v[16:17], 0, v[48:49]
	v_lshl_add_u64 v[20:21], v[18:19], 0, v[48:49]
	v_lshl_add_u64 v[24:25], v[24:25], 0, v[48:49]
	v_lshl_add_u64 v[28:29], v[26:27], 0, v[48:49]
	global_load_dwordx4 v[0:3], v[0:1], off nt
	s_nop 0
	global_load_dwordx4 v[4:7], v[4:5], off nt
	s_nop 0
	global_load_dwordx4 v[8:11], v[8:9], off nt
	s_nop 0
	global_load_dwordx4 v[12:15], v[12:13], off nt
	s_nop 0
	global_load_dwordx4 v[16:19], v[16:17], off nt
	s_nop 0
	global_load_dwordx4 v[20:23], v[20:21], off nt
	s_nop 0
	global_load_dwordx4 v[24:27], v[24:25], off nt
	s_nop 0
	global_load_dwordx4 v[28:31], v[28:29], off nt
	s_cmp_lg_u64 s[40:41], 0
	s_cselect_b64 s[88:89], -1, 0
	s_cmp_eq_u64 s[40:41], 0
	v_lshl_add_u64 v[102:103], v[102:103], 2, s[40:41]
	s_cbranch_scc1 .LBB0_1619
	global_load_dword v70, v[102:103], off
	global_load_dword v72, v[102:103], off offset:32

.LBB0_1631:
	s_waitcnt lgkmcnt(3)
	v_cvt_pk_bf16_f32 v102, v102, v103
	s_waitcnt lgkmcnt(2)
	v_cvt_pk_bf16_f32 v103, v104, v105
	s_waitcnt lgkmcnt(1)
	v_cvt_pk_bf16_f32 v104, v106, v107
	v_mad_u64_u32 v[106:107], s[20:21], v91, s65, 0
	s_waitcnt lgkmcnt(0)
	v_cvt_pk_bf16_f32 v105, v108, v109
	v_ashrrev_i32_e32 v93, 31, v91
	v_mov_b32_e32 v108, v107
	v_mad_u64_u32 v[108:109], s[20:21], v93, s65, v[108:109]
	v_mov_b32_e32 v107, v108
	s_lshl_b32 s88, s33, 6
	v_lshl_add_u64 v[106:107], v[106:107], 1, s[42:43]
	s_mov_b32 s47, s25
	s_ashr_i32 s89, s88, 31
	v_lshl_add_u64 v[106:107], s[46:47], 1, v[106:107]
	v_lshl_add_u64 v[106:107], s[88:89], 1, v[106:107]
	v_mov_b32_e32 v101, v49
	v_lshl_add_u64 v[106:107], v[106:107], 0, v[100:101]
	global_store_dwordx4 v[106:107], v[102:105], off nt
	s_nop 1
	ds_read2_b32 v[102:103], v81 offset0:8 offset1:41
	ds_read2_b32 v[104:105], v81 offset0:74 offset1:107
	ds_read2_b32 v[106:107], v81 offset0:140 offset1:173
	ds_read2_b32 v[108:109], v81 offset0:206 offset1:239
	v_cndmask_b32_e64 v91, 0, 1, s[40:41]
	v_cmp_ne_u32_e64 s[38:39], 1, v91
	s_andn2_b64 vcc, exec, s[40:41]
	v_or_b32_e32 v91, s94, v73
	s_cbranch_vccnz .LBB0_1633
	s_movk_i32 s6, 0xaff
	v_cmp_lt_i32_e32 vcc, s6, v91
	s_and_b32 s6, s94, 0x60
	s_nop 0
	v_cndmask_b32_e32 v93, 0, v209, vcc
	v_add_lshl_u32 v91, v93, v91, 1
	v_cndmask_b32_e64 v93, 0, 16, vcc
	v_and_b32_e32 v91, 0xffffff00, v91
	v_or_b32_e32 v93, s6, v93
	v_or3_b32 v91, v93, v91, v83

.LBB0_1637:
	s_waitcnt lgkmcnt(3)
	v_cvt_pk_bf16_f32 v102, v102, v103
	s_waitcnt lgkmcnt(2)
	v_cvt_pk_bf16_f32 v103, v104, v105
	s_waitcnt lgkmcnt(1)
	v_cvt_pk_bf16_f32 v104, v106, v107
	v_mad_u64_u32 v[106:107], s[20:21], v91, s65, 0
	s_waitcnt lgkmcnt(0)
	v_cvt_pk_bf16_f32 v105, v108, v109
	v_ashrrev_i32_e32 v93, 31, v91
	v_mov_b32_e32 v108, v107
	v_mad_u64_u32 v[108:109], s[20:21], v93, s65, v[108:109]
	v_mov_b32_e32 v107, v108
	v_lshl_add_u64 v[106:107], v[106:107], 1, s[42:43]
	v_lshl_add_u64 v[106:107], s[46:47], 1, v[106:107]
	v_lshl_add_u64 v[106:107], s[88:89], 1, v[106:107]
	v_mov_b32_e32 v101, v49
	v_lshl_add_u64 v[106:107], v[106:107], 0, v[100:101]
	global_store_dwordx4 v[106:107], v[102:105], off nt
	s_nop 1
	ds_read2_b32 v[102:103], v81 offset0:16 offset1:49
	ds_read2_b32 v[104:105], v81 offset0:82 offset1:115
	ds_read2_b32 v[106:107], v81 offset0:148 offset1:181
	ds_read2_b32 v[108:109], v81 offset0:214 offset1:247
	s_and_b64 vcc, exec, s[38:39]
	v_or_b32_e32 v91, s94, v75
	s_cbranch_vccnz .LBB0_1639
	s_movk_i32 s6, 0xaff
	v_cmp_lt_i32_e32 vcc, s6, v91
	s_and_b32 s6, s94, 0x60
	s_nop 0
	v_cndmask_b32_e32 v93, 0, v209, vcc
	v_add_lshl_u32 v91, v93, v91, 1
	v_cndmask_b32_e64 v93, 0, 16, vcc
	v_and_b32_e32 v91, 0xffffff00, v91
	v_or_b32_e32 v93, s6, v93
	v_or3_b32 v91, v93, v91, v85

.LBB0_1643:
	s_waitcnt lgkmcnt(3)
	v_cvt_pk_bf16_f32 v102, v102, v103
	s_waitcnt lgkmcnt(2)
	v_cvt_pk_bf16_f32 v103, v104, v105
	s_waitcnt lgkmcnt(1)
	v_cvt_pk_bf16_f32 v104, v106, v107
	v_mad_u64_u32 v[106:107], s[20:21], v91, s65, 0
	s_waitcnt lgkmcnt(0)
	v_cvt_pk_bf16_f32 v105, v108, v109
	v_ashrrev_i32_e32 v93, 31, v91
	v_mov_b32_e32 v108, v107
	v_mad_u64_u32 v[108:109], s[20:21], v93, s65, v[108:109]
	v_mov_b32_e32 v107, v108
	v_lshl_add_u64 v[106:107], v[106:107], 1, s[42:43]
	v_lshl_add_u64 v[106:107], s[46:47], 1, v[106:107]
	v_lshl_add_u64 v[106:107], s[88:89], 1, v[106:107]
	v_mov_b32_e32 v101, v49
	v_lshl_add_u64 v[106:107], v[106:107], 0, v[100:101]
	global_store_dwordx4 v[106:107], v[102:105], off nt
	s_nop 1
	ds_read2_b32 v[102:103], v81 offset0:24 offset1:57
	ds_read2_b32 v[104:105], v81 offset0:90 offset1:123
	ds_read2_b32 v[106:107], v81 offset0:156 offset1:189
	ds_read2_b32 v[108:109], v81 offset0:222 offset1:255
	s_and_b64 vcc, exec, s[38:39]
	v_or_b32_e32 v91, s94, v77
	s_cbranch_vccnz .LBB0_1645
	s_movk_i32 s6, 0xaff
	v_cmp_lt_i32_e32 vcc, s6, v91
	s_and_b32 s6, s94, 0x60
	s_nop 0
	v_cndmask_b32_e32 v93, 0, v209, vcc
	v_add_lshl_u32 v91, v93, v91, 1
	v_cndmask_b32_e64 v93, 0, 16, vcc
	v_and_b32_e32 v91, 0xffffff00, v91
	v_or_b32_e32 v93, s6, v93
	v_or3_b32 v91, v93, v91, v87

.LBB0_1702:
	s_lshr_b32 s6, s66, 5
	s_waitcnt vmcnt(7)
	v_cvt_f32_u32_e32 v0, s6
	s_sub_i32 s21, 0, s6
	s_abs_i32 s20, s52
	s_ashr_i32 s18, s52, 31
	v_rcp_iflag_f32_e32 v0, v0
	v_lshrrev_b32_e32 v71, 3, v69
	v_lshlrev_b32_e32 v1, 2, v69
	v_and_b32_e32 v2, 28, v1
	v_mul_f32_e32 v0, 0x4f7ffffe, v0
	v_cvt_u32_f32_e32 v0, v0
	v_lshlrev_b32_e32 v48, 2, v2
	s_waitcnt vmcnt(1)
	v_mov_b32_e32 v68, 1.0
	v_mov_b32_e32 v70, 1.0
	v_readfirstlane_b32 s26, v0
	s_mul_i32 s21, s21, s26
	s_mul_hi_u32 s21, s26, s21
	s_add_i32 s26, s26, s21
	s_mul_hi_u32 s21, s20, s26
	s_mul_i32 s26, s21, s6
	s_sub_i32 s20, s20, s26
	s_add_i32 s27, s21, 1
	s_sub_i32 s26, s20, s6
	s_cmp_ge_u32 s20, s6
	s_cselect_b32 s21, s27, s21
	s_cselect_b32 s20, s26, s20
	s_add_i32 s26, s21, 1
	s_cmp_ge_u32 s20, s6
	s_cselect_b32 s20, s26, s21
	s_xor_b32 s20, s20, s18
	s_sub_i32 s18, s20, s18
	s_mul_i32 s6, s18, s6
	s_waitcnt vmcnt(0)
	v_lshl_or_b32 v32, s18, 6, v71
	s_sub_i32 s6, s52, s6
	v_ashrrev_i32_e32 v33, 31, v32
	v_or_b32_e32 v2, 8, v32
	v_or_b32_e32 v8, 16, v32
	v_or_b32_e32 v10, 24, v32
	v_or_b32_e32 v16, 32, v32
	v_or_b32_e32 v18, 40, v32
	v_or_b32_e32 v24, 48, v32
	v_or_b32_e32 v26, 56, v32
	s_lshl_b32 s20, s6, 5
	v_mul_lo_u32 v28, v33, s66
	v_mad_u64_u32 v[0:1], s[26:27], v32, s66, 0
	v_mad_u64_u32 v[2:3], s[26:27], v2, s66, 0
	v_mad_u64_u32 v[8:9], s[26:27], v8, s66, 0
	v_mad_u64_u32 v[10:11], s[26:27], v10, s66, 0
	v_mad_u64_u32 v[16:17], s[26:27], v16, s66, 0
	v_mad_u64_u32 v[18:19], s[26:27], v18, s66, 0
	v_mad_u64_u32 v[24:25], s[26:27], v24, s66, 0
	v_mad_u64_u32 v[26:27], s[26:27], v26, s66, 0
	s_ashr_i32 s21, s20, 31
	v_add_u32_e32 v1, v1, v28
	v_add_u32_e32 v3, v3, v28
	v_add_u32_e32 v9, v9, v28
	v_add_u32_e32 v11, v11, v28
	v_add_u32_e32 v17, v17, v28
	v_add_u32_e32 v19, v19, v28
	v_add_u32_e32 v25, v25, v28
	v_add_u32_e32 v27, v27, v28
	v_lshl_add_u64 v[0:1], v[0:1], 2, s[38:39]
	s_lshl_b64 s[20:21], s[20:21], 2
	v_lshl_add_u64 v[2:3], v[2:3], 2, s[38:39]
	v_lshl_add_u64 v[8:9], v[8:9], 2, s[38:39]
	v_lshl_add_u64 v[10:11], v[10:11], 2, s[38:39]
	v_lshl_add_u64 v[16:17], v[16:17], 2, s[38:39]
	v_lshl_add_u64 v[18:19], v[18:19], 2, s[38:39]
	v_lshl_add_u64 v[24:25], v[24:25], 2, s[38:39]
	v_lshl_add_u64 v[26:27], v[26:27], 2, s[38:39]
	v_lshl_add_u64 v[0:1], v[0:1], 0, s[20:21]
	v_lshl_add_u64 v[2:3], v[2:3], 0, s[20:21]
	v_lshl_add_u64 v[8:9], v[8:9], 0, s[20:21]
	v_lshl_add_u64 v[10:11], v[10:11], 0, s[20:21]
	v_lshl_add_u64 v[16:17], v[16:17], 0, s[20:21]
	v_lshl_add_u64 v[18:19], v[18:19], 0, s[20:21]
	v_lshl_add_u64 v[24:25], v[24:25], 0, s[20:21]
	v_lshl_add_u64 v[26:27], v[26:27], 0, s[20:21]
	v_lshl_add_u64 v[0:1], v[0:1], 0, v[48:49]
	v_lshl_add_u64 v[4:5], v[2:3], 0, v[48:49]
	v_lshl_add_u64 v[8:9], v[8:9], 0, v[48:49]
	v_lshl_add_u64 v[12:13], v[10:11], 0, v[48:49]
	v_lshl_add_u64 v[16:17], v[16:17], 0, v[48:49]
	v_lshl_add_u64 v[20:21], v[18:19], 0, v[48:49]
	v_lshl_add_u64 v[24:25], v[24:25], 0, v[48:49]
	v_lshl_add_u64 v[28:29], v[26:27], 0, v[48:49]
	global_load_dwordx4 v[0:3], v[0:1], off nt
	s_nop 0
	global_load_dwordx4 v[4:7], v[4:5], off nt
	s_nop 0
	global_load_dwordx4 v[8:11], v[8:9], off nt
	s_nop 0
	global_load_dwordx4 v[12:15], v[12:13], off nt
	s_nop 0
	global_load_dwordx4 v[16:19], v[16:17], off nt
	s_nop 0
	global_load_dwordx4 v[20:23], v[20:21], off nt
	s_nop 0
	global_load_dwordx4 v[24:27], v[24:25], off nt
	s_nop 0
	global_load_dwordx4 v[28:31], v[28:29], off nt
	s_cmp_lg_u64 s[40:41], 0
	s_cselect_b64 s[42:43], -1, 0
	s_cmp_eq_u64 s[40:41], 0
	v_lshl_add_u64 v[32:33], v[32:33], 2, s[40:41]
	v_mov_b32_e32 v72, 1.0
	s_cbranch_scc1 .LBB0_1704
	global_load_dword v70, v[32:33], off
	global_load_dword v72, v[32:33], off offset:32

.LBB0_1712:
	s_waitcnt lgkmcnt(3)
	v_cvt_pk_bf16_f32 v102, v102, v103
	s_waitcnt lgkmcnt(2)
	v_cvt_pk_bf16_f32 v103, v104, v105
	s_waitcnt lgkmcnt(1)
	v_cvt_pk_bf16_f32 v104, v106, v107
	v_mad_u64_u32 v[106:107], s[20:21], v87, s65, 0
	s_waitcnt lgkmcnt(0)
	v_cvt_pk_bf16_f32 v105, v108, v109
	v_ashrrev_i32_e32 v89, 31, v87
	v_mov_b32_e32 v108, v107
	v_mad_u64_u32 v[108:109], s[20:21], v89, s65, v[108:109]
	v_mov_b32_e32 v107, v108
	v_lshl_add_u64 v[106:107], v[106:107], 1, s[42:43]
	v_lshl_add_u64 v[106:107], s[46:47], 1, v[106:107]
	v_lshl_add_u64 v[106:107], s[88:89], 1, v[106:107]
	v_mov_b32_e32 v101, v49
	v_lshl_add_u64 v[100:101], v[106:107], 0, v[100:101]
	global_store_dwordx4 v[100:101], v[102:105], off nt
	s_nop 1
	s_waitcnt lgkmcnt(0)
	s_and_b64 s[20:21], s[86:87], exec
	s_cselect_b32 s64, s18, s64

.LBB0_1763:
	s_lshr_b32 s6, s62, 5
	v_cvt_f32_u32_e32 v32, s6
	s_sub_i32 s26, 0, s6
	s_abs_i32 s21, s93
	s_ashr_i32 s20, s93, 31
	v_rcp_iflag_f32_e32 v32, v32
	v_mov_b32_e32 v84, 1.0
	v_mov_b32_e32 v88, 1.0
	v_mul_f32_e32 v32, 0x4f7ffffe, v32
	v_cvt_u32_f32_e32 v32, v32
	s_nop 0
	v_readfirstlane_b32 s27, v32
	s_mul_i32 s26, s26, s27
	s_mul_hi_u32 s26, s27, s26
	s_add_i32 s27, s27, s26
	s_mul_hi_u32 s26, s21, s27
	s_mul_i32 s27, s26, s6
	s_sub_i32 s21, s21, s27
	s_add_i32 s33, s26, 1
	s_sub_i32 s27, s21, s6
	s_cmp_ge_u32 s21, s6
	s_cselect_b32 s26, s33, s26
	s_cselect_b32 s21, s27, s21
	s_add_i32 s27, s26, 1
	s_cmp_ge_u32 s21, s6
	s_cselect_b32 s21, s27, s26
	s_xor_b32 s21, s21, s20
	s_sub_i32 s20, s21, s20
	s_mul_i32 s6, s20, s6
	v_lshl_or_b32 v86, s20, 6, v71
	s_sub_i32 s6, s93, s6
	v_ashrrev_i32_e32 v87, 31, v86
	v_or_b32_e32 v34, 8, v86
	v_or_b32_e32 v40, 16, v86
	v_or_b32_e32 v42, 24, v86
	v_or_b32_e32 v50, 32, v86
	v_or_b32_e32 v52, 40, v86
	v_or_b32_e32 v58, 48, v86
	v_or_b32_e32 v60, 56, v86
	s_lshl_b32 s20, s6, 5
	v_mul_lo_u32 v62, v87, s62
	v_mad_u64_u32 v[32:33], s[26:27], v86, s62, 0
	v_mad_u64_u32 v[34:35], s[26:27], v34, s62, 0
	v_mad_u64_u32 v[40:41], s[26:27], v40, s62, 0
	v_mad_u64_u32 v[42:43], s[26:27], v42, s62, 0
	v_mad_u64_u32 v[50:51], s[26:27], v50, s62, 0
	v_mad_u64_u32 v[52:53], s[26:27], v52, s62, 0
	v_mad_u64_u32 v[58:59], s[26:27], v58, s62, 0
	v_mad_u64_u32 v[60:61], s[26:27], v60, s62, 0
	s_ashr_i32 s21, s20, 31
	v_add_u32_e32 v33, v33, v62
	v_add_u32_e32 v35, v35, v62
	v_add_u32_e32 v41, v41, v62
	v_add_u32_e32 v43, v43, v62
	v_add_u32_e32 v51, v51, v62
	v_add_u32_e32 v53, v53, v62
	v_add_u32_e32 v59, v59, v62
	v_add_u32_e32 v61, v61, v62
	v_lshl_add_u64 v[32:33], v[32:33], 2, s[38:39]
	s_lshl_b64 s[20:21], s[20:21], 2
	v_lshl_add_u64 v[34:35], v[34:35], 2, s[38:39]
	v_lshl_add_u64 v[40:41], v[40:41], 2, s[38:39]
	v_lshl_add_u64 v[42:43], v[42:43], 2, s[38:39]
	v_lshl_add_u64 v[50:51], v[50:51], 2, s[38:39]
	v_lshl_add_u64 v[52:53], v[52:53], 2, s[38:39]
	v_lshl_add_u64 v[58:59], v[58:59], 2, s[38:39]
	v_lshl_add_u64 v[60:61], v[60:61], 2, s[38:39]
	v_lshl_add_u64 v[32:33], v[32:33], 0, s[20:21]
	v_lshl_add_u64 v[34:35], v[34:35], 0, s[20:21]
	v_lshl_add_u64 v[40:41], v[40:41], 0, s[20:21]
	v_lshl_add_u64 v[42:43], v[42:43], 0, s[20:21]
	v_lshl_add_u64 v[50:51], v[50:51], 0, s[20:21]
	v_lshl_add_u64 v[52:53], v[52:53], 0, s[20:21]
	v_lshl_add_u64 v[58:59], v[58:59], 0, s[20:21]
	v_lshl_add_u64 v[60:61], v[60:61], 0, s[20:21]
	v_lshl_add_u64 v[32:33], v[32:33], 0, v[48:49]
	v_lshl_add_u64 v[36:37], v[34:35], 0, v[48:49]
	v_lshl_add_u64 v[40:41], v[40:41], 0, v[48:49]
	v_lshl_add_u64 v[44:45], v[42:43], 0, v[48:49]
	v_lshl_add_u64 v[50:51], v[50:51], 0, v[48:49]
	v_lshl_add_u64 v[54:55], v[52:53], 0, v[48:49]
	v_lshl_add_u64 v[58:59], v[58:59], 0, v[48:49]
	v_lshl_add_u64 v[62:63], v[60:61], 0, v[48:49]
	global_load_dwordx4 v[32:35], v[32:33], off nt
	s_nop 0
	global_load_dwordx4 v[36:39], v[36:37], off nt
	s_nop 0
	global_load_dwordx4 v[40:43], v[40:41], off nt
	s_nop 0
	global_load_dwordx4 v[44:47], v[44:45], off nt
	s_nop 0
	global_load_dwordx4 v[50:53], v[50:51], off nt
	s_nop 0
	global_load_dwordx4 v[54:57], v[54:55], off nt
	s_nop 0
	global_load_dwordx4 v[58:61], v[58:59], off nt
	s_nop 0
	global_load_dwordx4 v[62:65], v[62:63], off nt
	s_cmp_lg_u64 s[40:41], 0
	s_cselect_b64 s[88:89], -1, 0
	s_cmp_eq_u64 s[40:41], 0
	v_lshl_add_u64 v[100:101], v[86:87], 2, s[40:41]
	v_mov_b32_e32 v86, 1.0
	s_cbranch_scc1 .LBB0_1765
	global_load_dword v86, v[100:101], off
	global_load_dword v88, v[100:101], off offset:32

.LBB0_1777:
	s_waitcnt lgkmcnt(3)
	v_cvt_pk_bf16_f32 v118, v100, v101
	v_mad_u64_u32 v[100:101], s[20:21], v108, s53, 0
	s_waitcnt lgkmcnt(2)
	v_cvt_pk_bf16_f32 v119, v102, v103
	v_ashrrev_i32_e32 v103, 31, v108
	v_mov_b32_e32 v102, v101
	v_mad_u64_u32 v[102:103], s[20:21], v103, s53, v[102:103]
	v_mov_b32_e32 v101, v102
	s_lshl_b32 s88, s6, 6
	v_lshl_add_u64 v[100:101], v[100:101], 1, s[44:45]
	s_ashr_i32 s89, s88, 31
	v_lshl_add_u64 v[100:101], s[24:25], 1, v[100:101]
	v_lshl_add_u64 v[102:103], s[88:89], 1, v[100:101]
	v_lshlrev_b32_e32 v100, 1, v66
	v_mov_b32_e32 v101, v49
	s_waitcnt lgkmcnt(1)
	v_cvt_pk_bf16_f32 v120, v104, v105
	s_waitcnt lgkmcnt(0)
	v_cvt_pk_bf16_f32 v121, v106, v107
	v_lshl_add_u64 v[102:103], v[102:103], 0, v[100:101]
	global_store_dwordx4 v[102:103], v[118:121], off nt
	s_nop 1
	ds_read2_b32 v[102:103], v77 offset0:8 offset1:41
	ds_read2_b32 v[104:105], v77 offset0:74 offset1:107
	ds_read2_b32 v[106:107], v77 offset0:140 offset1:173
	ds_read2_b32 v[108:109], v77 offset0:206 offset1:239
	v_cndmask_b32_e64 v101, 0, 1, s[40:41]
	v_cmp_ne_u32_e64 s[38:39], 1, v101
	s_andn2_b64 vcc, exec, s[40:41]
	v_or_b32_e32 v101, s33, v67
	s_cbranch_vccnz .LBB0_1779
	s_movk_i32 s6, 0xaff
	v_cmp_lt_i32_e32 vcc, s6, v101
	s_and_b32 s6, s33, 0x60
	s_nop 0
	v_cndmask_b32_e32 v117, 0, v209, vcc
	v_add_lshl_u32 v101, v117, v101, 1
	v_cndmask_b32_e64 v117, 0, 16, vcc
	v_and_b32_e32 v101, 0xffffff00, v101
	v_or_b32_e32 v117, s6, v117
	v_or3_b32 v101, v117, v101, v79

.LBB0_1783:
	s_waitcnt lgkmcnt(3)
	v_cvt_pk_bf16_f32 v102, v102, v103
	s_waitcnt lgkmcnt(2)
	v_cvt_pk_bf16_f32 v103, v104, v105
	s_waitcnt lgkmcnt(1)
	v_cvt_pk_bf16_f32 v104, v106, v107
	v_mad_u64_u32 v[106:107], s[20:21], v101, s53, 0
	s_waitcnt lgkmcnt(0)
	v_cvt_pk_bf16_f32 v105, v108, v109
	v_ashrrev_i32_e32 v109, 31, v101
	v_mov_b32_e32 v108, v107
	v_mad_u64_u32 v[108:109], s[20:21], v109, s53, v[108:109]
	v_mov_b32_e32 v107, v108
	v_lshl_add_u64 v[106:107], v[106:107], 1, s[44:45]
	v_lshl_add_u64 v[106:107], s[24:25], 1, v[106:107]
	v_lshl_add_u64 v[106:107], s[88:89], 1, v[106:107]
	v_mov_b32_e32 v101, v49
	v_lshl_add_u64 v[106:107], v[106:107], 0, v[100:101]
	global_store_dwordx4 v[106:107], v[102:105], off nt
	s_nop 1
	ds_read2_b32 v[102:103], v77 offset0:16 offset1:49
	ds_read2_b32 v[104:105], v77 offset0:82 offset1:115
	ds_read2_b32 v[106:107], v77 offset0:148 offset1:181
	ds_read2_b32 v[108:109], v77 offset0:214 offset1:247
	s_and_b64 vcc, exec, s[38:39]
	v_or_b32_e32 v101, s33, v69
	s_cbranch_vccnz .LBB0_1785
	s_movk_i32 s6, 0xaff
	v_cmp_lt_i32_e32 vcc, s6, v101
	s_and_b32 s6, s33, 0x60
	s_nop 0
	v_cndmask_b32_e32 v117, 0, v209, vcc
	v_add_lshl_u32 v101, v117, v101, 1
	v_cndmask_b32_e64 v117, 0, 16, vcc
	v_and_b32_e32 v101, 0xffffff00, v101
	v_or_b32_e32 v117, s6, v117
	v_or3_b32 v101, v117, v101, v81

.LBB0_1789:
	s_waitcnt lgkmcnt(3)
	v_cvt_pk_bf16_f32 v102, v102, v103
	s_waitcnt lgkmcnt(2)
	v_cvt_pk_bf16_f32 v103, v104, v105
	s_waitcnt lgkmcnt(1)
	v_cvt_pk_bf16_f32 v104, v106, v107
	v_mad_u64_u32 v[106:107], s[20:21], v101, s53, 0
	s_waitcnt lgkmcnt(0)
	v_cvt_pk_bf16_f32 v105, v108, v109
	v_ashrrev_i32_e32 v109, 31, v101
	v_mov_b32_e32 v108, v107
	v_mad_u64_u32 v[108:109], s[20:21], v109, s53, v[108:109]
	v_mov_b32_e32 v107, v108
	v_lshl_add_u64 v[106:107], v[106:107], 1, s[44:45]
	v_lshl_add_u64 v[106:107], s[24:25], 1, v[106:107]
	v_lshl_add_u64 v[106:107], s[88:89], 1, v[106:107]
	v_mov_b32_e32 v101, v49
	v_lshl_add_u64 v[106:107], v[106:107], 0, v[100:101]
	global_store_dwordx4 v[106:107], v[102:105], off nt
	s_nop 1
	ds_read2_b32 v[102:103], v77 offset0:24 offset1:57
	ds_read2_b32 v[104:105], v77 offset0:90 offset1:123
	ds_read2_b32 v[106:107], v77 offset0:156 offset1:189
	ds_read2_b32 v[108:109], v77 offset0:222 offset1:255
	s_and_b64 vcc, exec, s[38:39]
	v_or_b32_e32 v101, s33, v73
	s_cbranch_vccnz .LBB0_1791
	s_movk_i32 s6, 0xaff
	v_cmp_lt_i32_e32 vcc, s6, v101
	s_and_b32 s6, s33, 0x60
	s_nop 0
	v_cndmask_b32_e32 v117, 0, v209, vcc
	v_add_lshl_u32 v101, v117, v101, 1
	v_cndmask_b32_e64 v117, 0, 16, vcc
	v_and_b32_e32 v101, 0xffffff00, v101
	v_or_b32_e32 v117, s6, v117
	v_or3_b32 v101, v117, v101, v83

.LBB0_1795:
	s_waitcnt lgkmcnt(3)
	v_cvt_pk_bf16_f32 v102, v102, v103
	s_waitcnt lgkmcnt(2)
	v_cvt_pk_bf16_f32 v103, v104, v105
	s_waitcnt lgkmcnt(1)
	v_cvt_pk_bf16_f32 v104, v106, v107
	v_mad_u64_u32 v[106:107], s[20:21], v101, s53, 0
	s_waitcnt lgkmcnt(0)
	v_cvt_pk_bf16_f32 v105, v108, v109
	v_ashrrev_i32_e32 v109, 31, v101
	v_mov_b32_e32 v108, v107
	v_mad_u64_u32 v[108:109], s[20:21], v109, s53, v[108:109]
	v_mov_b32_e32 v107, v108
	v_lshl_add_u64 v[106:107], v[106:107], 1, s[44:45]
	v_lshl_add_u64 v[106:107], s[24:25], 1, v[106:107]
	v_lshl_add_u64 v[106:107], s[88:89], 1, v[106:107]
	v_mov_b32_e32 v101, v49
	v_lshl_add_u64 v[106:107], v[106:107], 0, v[100:101]
	global_store_dwordx4 v[106:107], v[102:105], off nt
	s_nop 1
	s_waitcnt lgkmcnt(0)
	s_andn2_b64 vcc, exec, s[86:87]
	s_mov_b64 s[86:87], 0
	s_cbranch_vccnz .LBB0_1713
	v_readlane_b32 s20, v255, 19
	s_add_i32 s18, s18, s20
	s_cmp_lt_i32 s18, s9
	s_cselect_b64 s[86:87], -1, 0
	s_cmp_ge_i32 s18, s9
	v_readlane_b32 s21, v255, 20
	s_cbranch_scc1 .LBB0_1854
	s_cmpk_gt_i32 s18, 0xaff
	s_mov_b64 s[88:89], -1
	s_cbranch_scc0 .LBB0_1844
	s_cmpk_gt_u32 s18, 0x15ff
	s_cbranch_scc0 .LBB0_1841
	s_cmpk_gt_u32 s18, 0x1b7f
	s_cbranch_scc0 .LBB0_1838
	s_cmpk_gt_u32 s18, 0x20ff
	s_cbranch_scc0 .LBB0_1835
	s_add_i32 s33, s18, 0xffffdf00
	s_cmp_ge_i32 s33, s92
	s_cbranch_scc0 .LBB0_1827
	s_sub_i32 s47, s33, s92
	s_cmpk_gt_i32 s47, 0x1ff
	s_cbranch_scc0 .LBB0_1820
	v_readlane_b32 s20, v255, 35
	v_readlane_b32 s21, v255, 36
	s_add_i32 s90, s47, 0xfffffe00
	s_mov_b64 s[40:41], -1
	s_and_b64 vcc, exec, s[20:21]
	s_cbranch_vccz .LBB0_1813
	s_cmpk_gt_u32 s47, 0x20f
	s_cbranch_scc0 .LBB0_1810
	s_cmpk_gt_u32 s47, 0x21f
	s_cbranch_scc0 .LBB0_1807
	s_add_i32 s52, s47, 0xfffffde0
	v_readlane_b32 s26, v255, 39
	s_load_dwordx2 s[20:21], s[0:1], 0x98
	s_waitcnt lgkmcnt(0)
	v_readlane_b32 s27, v255, 40
	s_add_u32 s38, s20, s26
	s_addc_u32 s39, s21, s27
	s_mov_b64 s[40:41], 0

.LBB0_1846:
	s_lshr_b32 s6, s66, 5
	v_cvt_f32_u32_e32 v0, s6
	s_sub_i32 s26, 0, s6
	s_abs_i32 s21, s52
	s_ashr_i32 s20, s52, 31
	v_rcp_iflag_f32_e32 v0, v0
	v_mov_b32_e32 v68, 1.0
	v_mov_b32_e32 v70, 1.0
	v_mov_b32_e32 v72, 1.0
	v_mul_f32_e32 v0, 0x4f7ffffe, v0
	v_cvt_u32_f32_e32 v0, v0
	s_nop 0
	v_readfirstlane_b32 s27, v0
	s_mul_i32 s26, s26, s27
	s_mul_hi_u32 s26, s27, s26
	s_add_i32 s27, s27, s26
	s_mul_hi_u32 s26, s21, s27
	s_mul_i32 s27, s26, s6
	s_sub_i32 s21, s21, s27
	s_add_i32 s33, s26, 1
	s_sub_i32 s27, s21, s6
	s_cmp_ge_u32 s21, s6
	s_cselect_b32 s26, s33, s26
	s_cselect_b32 s21, s27, s21
	s_add_i32 s27, s26, 1
	s_cmp_ge_u32 s21, s6
	s_cselect_b32 s21, s27, s26
	s_xor_b32 s21, s21, s20
	s_sub_i32 s20, s21, s20
	s_mul_i32 s6, s20, s6
	v_lshl_or_b32 v102, s20, 6, v71
	s_sub_i32 s6, s52, s6
	v_ashrrev_i32_e32 v103, 31, v102
	v_or_b32_e32 v2, 8, v102
	v_or_b32_e32 v8, 16, v102
	v_or_b32_e32 v10, 24, v102
	v_or_b32_e32 v16, 32, v102
	v_or_b32_e32 v18, 40, v102
	v_or_b32_e32 v24, 48, v102
	v_or_b32_e32 v26, 56, v102
	s_lshl_b32 s20, s6, 5
	v_mul_lo_u32 v28, v103, s66
	v_mad_u64_u32 v[0:1], s[26:27], v102, s66, 0
	v_mad_u64_u32 v[2:3], s[26:27], v2, s66, 0
	v_mad_u64_u32 v[8:9], s[26:27], v8, s66, 0
	v_mad_u64_u32 v[10:11], s[26:27], v10, s66, 0
	v_mad_u64_u32 v[16:17], s[26:27], v16, s66, 0
	v_mad_u64_u32 v[18:19], s[26:27], v18, s66, 0
	v_mad_u64_u32 v[24:25], s[26:27], v24, s66, 0
	v_mad_u64_u32 v[26:27], s[26:27], v26, s66, 0
	s_ashr_i32 s21, s20, 31
	v_add_u32_e32 v1, v1, v28
	v_add_u32_e32 v3, v3, v28
	v_add_u32_e32 v9, v9, v28
	v_add_u32_e32 v11, v11, v28
	v_add_u32_e32 v17, v17, v28
	v_add_u32_e32 v19, v19, v28
	v_add_u32_e32 v25, v25, v28
	v_add_u32_e32 v27, v27, v28
	v_lshl_add_u64 v[0:1], v[0:1], 2, s[38:39]
	s_lshl_b64 s[20:21], s[20:21], 2
	v_lshl_add_u64 v[2:3], v[2:3], 2, s[38:39]
	v_lshl_add_u64 v[8:9], v[8:9], 2, s[38:39]
	v_lshl_add_u64 v[10:11], v[10:11], 2, s[38:39]
	v_lshl_add_u64 v[16:17], v[16:17], 2, s[38:39]
	v_lshl_add_u64 v[18:19], v[18:19], 2, s[38:39]
	v_lshl_add_u64 v[24:25], v[24:25], 2, s[38:39]
	v_lshl_add_u64 v[26:27], v[26:27], 2, s[38:39]
	v_lshl_add_u64 v[0:1], v[0:1], 0, s[20:21]
	v_lshl_add_u64 v[2:3], v[2:3], 0, s[20:21]
	v_lshl_add_u64 v[8:9], v[8:9], 0, s[20:21]
	v_lshl_add_u64 v[10:11], v[10:11], 0, s[20:21]
	v_lshl_add_u64 v[16:17], v[16:17], 0, s[20:21]
	v_lshl_add_u64 v[18:19], v[18:19], 0, s[20:21]
	v_lshl_add_u64 v[24:25], v[24:25], 0, s[20:21]
	v_lshl_add_u64 v[26:27], v[26:27], 0, s[20:21]
	v_lshl_add_u64 v[0:1], v[0:1], 0, v[48:49]
	v_lshl_add_u64 v[4:5], v[2:3], 0, v[48:49]
	v_lshl_add_u64 v[8:9], v[8:9], 0, v[48:49]
	v_lshl_add_u64 v[12:13], v[10:11], 0, v[48:49]
	v_lshl_add_u64 v[16:17], v[16:17], 0, v[48:49]
	v_lshl_add_u64 v[20:21], v[18:19], 0, v[48:49]
	v_lshl_add_u64 v[24:25], v[24:25], 0, v[48:49]
	v_lshl_add_u64 v[28:29], v[26:27], 0, v[48:49]
	global_load_dwordx4 v[0:3], v[0:1], off nt
	s_nop 0
	global_load_dwordx4 v[4:7], v[4:5], off nt
	s_nop 0
	global_load_dwordx4 v[8:11], v[8:9], off nt
	s_nop 0
	global_load_dwordx4 v[12:15], v[12:13], off nt
	s_nop 0
	global_load_dwordx4 v[16:19], v[16:17], off nt
	s_nop 0
	global_load_dwordx4 v[20:23], v[20:21], off nt
	s_nop 0
	global_load_dwordx4 v[24:27], v[24:25], off nt
	s_nop 0
	global_load_dwordx4 v[28:31], v[28:29], off nt
	s_cmp_lg_u64 s[40:41], 0
	s_cselect_b64 s[88:89], -1, 0
	s_cmp_eq_u64 s[40:41], 0
	v_lshl_add_u64 v[102:103], v[102:103], 2, s[40:41]
	s_cbranch_scc1 .LBB0_1848
	global_load_dword v70, v[102:103], off
	global_load_dword v72, v[102:103], off offset:32

.LBB0_1860:
	s_waitcnt lgkmcnt(3)
	v_cvt_pk_bf16_f32 v102, v102, v103
	s_waitcnt lgkmcnt(2)
	v_cvt_pk_bf16_f32 v103, v104, v105
	s_waitcnt lgkmcnt(1)
	v_cvt_pk_bf16_f32 v104, v106, v107
	v_mad_u64_u32 v[106:107], s[20:21], v87, s65, 0
	s_waitcnt lgkmcnt(0)
	v_cvt_pk_bf16_f32 v105, v108, v109
	v_ashrrev_i32_e32 v89, 31, v87
	v_mov_b32_e32 v108, v107
	v_mad_u64_u32 v[108:109], s[20:21], v89, s65, v[108:109]
	v_mov_b32_e32 v107, v108
	s_lshl_b32 s88, s33, 6
	v_lshl_add_u64 v[106:107], v[106:107], 1, s[42:43]
	s_mov_b32 s47, s25
	s_ashr_i32 s89, s88, 31
	v_lshl_add_u64 v[106:107], s[46:47], 1, v[106:107]
	v_lshl_add_u64 v[106:107], s[88:89], 1, v[106:107]
	v_mov_b32_e32 v101, v49
	v_lshl_add_u64 v[106:107], v[106:107], 0, v[100:101]
	global_store_dwordx4 v[106:107], v[102:105], off nt
	s_nop 1
	ds_read2_b32 v[102:103], v77 offset0:8 offset1:41
	ds_read2_b32 v[104:105], v77 offset0:74 offset1:107
	ds_read2_b32 v[106:107], v77 offset0:140 offset1:173
	ds_read2_b32 v[108:109], v77 offset0:206 offset1:239
	v_cndmask_b32_e64 v87, 0, 1, s[40:41]
	v_cmp_ne_u32_e64 s[38:39], 1, v87
	s_andn2_b64 vcc, exec, s[40:41]
	v_or_b32_e32 v87, s94, v67
	s_cbranch_vccnz .LBB0_1862
	s_movk_i32 s6, 0xaff
	v_cmp_lt_i32_e32 vcc, s6, v87
	s_and_b32 s6, s94, 0x60
	s_nop 0
	v_cndmask_b32_e32 v89, 0, v209, vcc
	v_add_lshl_u32 v87, v89, v87, 1
	v_cndmask_b32_e64 v89, 0, 16, vcc
	v_and_b32_e32 v87, 0xffffff00, v87
	v_or_b32_e32 v89, s6, v89
	v_or3_b32 v87, v89, v87, v79

.LBB0_1866:
	s_waitcnt lgkmcnt(3)
	v_cvt_pk_bf16_f32 v102, v102, v103
	s_waitcnt lgkmcnt(2)
	v_cvt_pk_bf16_f32 v103, v104, v105
	s_waitcnt lgkmcnt(1)
	v_cvt_pk_bf16_f32 v104, v106, v107
	v_mad_u64_u32 v[106:107], s[20:21], v87, s65, 0
	s_waitcnt lgkmcnt(0)
	v_cvt_pk_bf16_f32 v105, v108, v109
	v_ashrrev_i32_e32 v89, 31, v87
	v_mov_b32_e32 v108, v107
	v_mad_u64_u32 v[108:109], s[20:21], v89, s65, v[108:109]
	v_mov_b32_e32 v107, v108
	v_lshl_add_u64 v[106:107], v[106:107], 1, s[42:43]
	v_lshl_add_u64 v[106:107], s[46:47], 1, v[106:107]
	v_lshl_add_u64 v[106:107], s[88:89], 1, v[106:107]
	v_mov_b32_e32 v101, v49
	v_lshl_add_u64 v[106:107], v[106:107], 0, v[100:101]
	global_store_dwordx4 v[106:107], v[102:105], off nt
	s_nop 1
	ds_read2_b32 v[102:103], v77 offset0:16 offset1:49
	ds_read2_b32 v[104:105], v77 offset0:82 offset1:115
	ds_read2_b32 v[106:107], v77 offset0:148 offset1:181
	ds_read2_b32 v[108:109], v77 offset0:214 offset1:247
	s_and_b64 vcc, exec, s[38:39]
	v_or_b32_e32 v87, s94, v69
	s_cbranch_vccnz .LBB0_1868
	s_movk_i32 s6, 0xaff
	v_cmp_lt_i32_e32 vcc, s6, v87
	s_and_b32 s6, s94, 0x60
	s_nop 0
	v_cndmask_b32_e32 v89, 0, v209, vcc
	v_add_lshl_u32 v87, v89, v87, 1
	v_cndmask_b32_e64 v89, 0, 16, vcc
	v_and_b32_e32 v87, 0xffffff00, v87
	v_or_b32_e32 v89, s6, v89
	v_or3_b32 v87, v89, v87, v81

.LBB0_1872:
	s_waitcnt lgkmcnt(3)
	v_cvt_pk_bf16_f32 v102, v102, v103
	s_waitcnt lgkmcnt(2)
	v_cvt_pk_bf16_f32 v103, v104, v105
	s_waitcnt lgkmcnt(1)
	v_cvt_pk_bf16_f32 v104, v106, v107
	v_mad_u64_u32 v[106:107], s[20:21], v87, s65, 0
	s_waitcnt lgkmcnt(0)
	v_cvt_pk_bf16_f32 v105, v108, v109
	v_ashrrev_i32_e32 v89, 31, v87
	v_mov_b32_e32 v108, v107
	v_mad_u64_u32 v[108:109], s[20:21], v89, s65, v[108:109]
	v_mov_b32_e32 v107, v108
	v_lshl_add_u64 v[106:107], v[106:107], 1, s[42:43]
	v_lshl_add_u64 v[106:107], s[46:47], 1, v[106:107]
	v_lshl_add_u64 v[106:107], s[88:89], 1, v[106:107]
	v_mov_b32_e32 v101, v49
	v_lshl_add_u64 v[106:107], v[106:107], 0, v[100:101]
	global_store_dwordx4 v[106:107], v[102:105], off nt
	s_nop 1
	ds_read2_b32 v[102:103], v77 offset0:24 offset1:57
	ds_read2_b32 v[104:105], v77 offset0:90 offset1:123
	ds_read2_b32 v[106:107], v77 offset0:156 offset1:189
	ds_read2_b32 v[108:109], v77 offset0:222 offset1:255
	s_and_b64 vcc, exec, s[38:39]
	v_or_b32_e32 v87, s94, v73
	s_cbranch_vccnz .LBB0_1874
	s_movk_i32 s6, 0xaff
	v_cmp_lt_i32_e32 vcc, s6, v87
	s_and_b32 s6, s94, 0x60
	s_nop 0
	v_cndmask_b32_e32 v89, 0, v209, vcc
	v_add_lshl_u32 v87, v89, v87, 1
	v_cndmask_b32_e64 v89, 0, 16, vcc
	v_and_b32_e32 v87, 0xffffff00, v87
	v_or_b32_e32 v89, s6, v89
	v_or3_b32 v87, v89, v87, v83
